# EpiResid epilogues (5 GEMM+residual phases): second-half residual loads hoisted beside first-half loads with counted vmcnt
# baseline (speedup 1.0000x reference)
; __device__ __forceinline__ u32x4 pack8(const f32x4 a, const f32x4 b) { u32x4 w; w.x = cvt_pk_bf16(a[0], a[1]); w.y = cvt_pk_bf16(a[2], a[3]); w.z = cvt_pk_bf16(b[0], b[1]); w.w = cvt_pk_bf16(b[2], b[3]); return w; }
; __device__ __forceinline__ void ss_add(ssq_t* p, float sq) { __hip_atomic_fetch_add(p, (ssq_t)(sq * 16777216.0f), __ATOMIC_RELAXED, __HIP_MEMORY_SCOPE_AGENT); }
; __device__ __forceinline__ float dot4(const f32x4 a) { return (a[0] * a[0] + a[1] * a[1]) + (a[2] * a[2] + a[3] * a[3]); }
;     __device__ __forceinline__ void operator()(const f32x4 (&acc)[2][2][4][2], const Unit& u, int wr, int wc, int fr, int fq) const {
;     ...
;             for (int m = 0; m < 4; ++m) { const int row = row0 + ai * HALF + m * 16; const size_t off = (size_t)row * 2048 + col0; float sq = 0.f;
; #pragma unroll
;                 for (int bj = 0; bj < 2; ++bj) {
;                     const f32x4 x0 = __builtin_nontemporal_load((const f32x4*)(xin + off + bj * HALF)), x1 = __builtin_nontemporal_load((const f32x4*)(xin + off + bj * HALF + 4));
;                     const f32x4 v0 = x0 + acc[ai][bj][m][0] * alpha, v1 = x1 + acc[ai][bj][m][1] * alpha;
;                     __builtin_nontemporal_store(v0, (f32x4*)(xout + off + bj * HALF)); __builtin_nontemporal_store(v1, (f32x4*)(xout + off + bj * HALF + 4));
;                     if (WRITE_XB) *(u32x4*)(xb + off + bj * HALF) = pack8(v0, v1); sq += dot4(v0) + dot4(v1); }
;                 sq += __shfl_xor(sq, 16); sq += __shfl_xor(sq, 32);
;                 if (fq == 0) ss_add(ssout + row, sq); }
.LBB0_586:
	v_lshl_add_u32 v146, s36, 8, v148
	v_lshl_add_u32 v144, s37, 8, v150
	v_ashrrev_i32_e32 v147, 31, v146
	v_ashrrev_i32_e32 v145, 31, v144
	v_lshlrev_b64 v[156:157], 11, v[146:147]
	v_lshl_add_u64 v[164:165], v[156:157], 0, v[144:145]
	v_lshlrev_b64 v[166:167], 2, v[164:165]
	v_lshl_add_u64 v[168:169], s[52:53], 0, v[166:167]
	global_load_dwordx4 v[156:159], v[168:169], off nt
	global_load_dwordx4 v[160:163], v[168:169], off offset:16 nt
	global_load_dwordx4 v[176:179], v[168:169], off offset:512 nt
	global_load_dwordx4 v[180:183], v[168:169], off offset:528 nt
	v_lshl_add_u64 v[170:171], v[164:165], 1, s[46:47]
	v_lshl_add_u64 v[172:173], s[28:29], 0, v[166:167]
	s_waitcnt vmcnt(2)
	v_pk_fma_f32 v[126:127], v[126:127], 0.5, v[158:159] op_sel_hi:[1,0,1]
	v_pk_fma_f32 v[124:125], v[124:125], 0.5, v[156:157] op_sel_hi:[1,0,1]
	v_pk_fma_f32 v[158:159], v[122:123], 0.5, v[162:163] op_sel_hi:[1,0,1]
	v_pk_fma_f32 v[156:157], v[120:121], 0.5, v[160:161] op_sel_hi:[1,0,1]
	v_cvt_pk_bf16_f32 v120, v124, v125
	v_cvt_pk_bf16_f32 v121, v126, v127
	v_cvt_pk_bf16_f32 v122, v156, v157
	v_cvt_pk_bf16_f32 v123, v158, v159
	global_store_dwordx4 v[172:173], v[124:127], off nt
	global_store_dwordx4 v[172:173], v[156:159], off offset:16 nt
	global_store_dwordx4 v[170:171], v[120:123], off
	s_nop 1
	v_and_b32_e32 v121, 64, v154
	v_xor_b32_e32 v120, 16, v154
	v_add_u32_e32 v121, 64, v121
	v_xor_b32_e32 v122, 32, v154
	v_cmp_lt_i32_e32 vcc, v120, v121
	v_mul_f32_e32 v123, v127, v127
	v_mul_f32_e32 v127, v159, v159
	v_cndmask_b32_e32 v120, v154, v120, vcc
	v_cmp_lt_i32_e32 vcc, v122, v121
	v_fmac_f32_e32 v123, v126, v126
	v_fmac_f32_e32 v127, v158, v158
	v_cndmask_b32_e32 v121, v154, v122, vcc
	v_mul_f32_e32 v122, v125, v125
	v_mul_f32_e32 v125, v157, v157
	v_fmac_f32_e32 v122, v124, v124
	v_fmac_f32_e32 v125, v156, v156
	v_add_f32_e32 v122, v122, v123
	v_add_f32_e32 v123, v125, v127
	v_add_f32_e32 v126, v122, v123
	v_lshlrev_b32_e32 v120, 2, v120
	s_waitcnt vmcnt(4)
	v_pk_fma_f32 v[118:119], v[118:119], 0.5, v[178:179] op_sel_hi:[1,0,1]
	v_pk_fma_f32 v[116:117], v[116:117], 0.5, v[176:177] op_sel_hi:[1,0,1]
	s_waitcnt vmcnt(3)
	v_pk_fma_f32 v[124:125], v[114:115], 0.5, v[182:183] op_sel_hi:[1,0,1]
	v_pk_fma_f32 v[122:123], v[112:113], 0.5, v[180:181] op_sel_hi:[1,0,1]
	v_mul_f32_e32 v112, v117, v117
	v_mul_f32_e32 v113, v119, v119
	v_mul_f32_e32 v114, v123, v123
	v_mul_f32_e32 v115, v125, v125
	v_fmac_f32_e32 v112, v116, v116
	v_fmac_f32_e32 v113, v118, v118
	v_fmac_f32_e32 v114, v122, v122
	v_fmac_f32_e32 v115, v124, v124
	v_add_f32_e32 v112, v112, v113
	v_add_f32_e32 v113, v114, v115
	v_add_f32_e32 v112, v112, v113
	v_add_f32_e32 v112, v126, v112
	ds_bpermute_b32 v113, v120, v112
	v_lshlrev_b32_e32 v114, 2, v121
	global_store_dwordx4 v[172:173], v[116:119], off offset:512 nt
	global_store_dwordx4 v[172:173], v[122:125], off offset:528 nt
	s_waitcnt lgkmcnt(0)
	v_add_f32_e32 v112, v112, v113
	ds_bpermute_b32 v113, v114, v112
	v_cvt_pk_bf16_f32 v116, v116, v117
	v_cvt_pk_bf16_f32 v117, v118, v119
	v_cvt_pk_bf16_f32 v118, v122, v123
	v_cvt_pk_bf16_f32 v119, v124, v125
	global_store_dwordx4 v[170:171], v[116:119], off offset:256
	s_and_saveexec_b64 s[36:37], s[2:3]
	s_cbranch_execz .LBB0_588
	s_waitcnt lgkmcnt(0)
	v_add_f32_e32 v112, v112, v113
	v_mul_f32_e32 v112, 0x4b800000, v112
	v_trunc_f32_e32 v112, v112
	v_mul_f32_e32 v113, 0x2f800000, v112
	v_floor_f32_e32 v113, v113
	v_fmac_f32_e32 v112, 0xcf800000, v113
	v_cvt_u32_f32_e32 v112, v112
	v_cvt_u32_f32_e32 v113, v113
	v_lshl_add_u64 v[116:117], v[146:147], 3, s[18:19]
	global_atomic_add_x2 v[116:117], v[112:113], off
.LBB0_588:
	s_or_b64 exec, exec, s[36:37]
	v_or_b32_e32 v112, 16, v146
	s_waitcnt lgkmcnt(0)
	v_ashrrev_i32_e32 v113, 31, v112
	v_lshlrev_b64 v[116:117], 11, v[112:113]
	v_lshl_add_u64 v[126:127], v[116:117], 0, v[144:145]
	v_lshlrev_b64 v[156:157], 2, v[126:127]
	v_lshl_add_u64 v[158:159], s[52:53], 0, v[156:157]
	global_load_dwordx4 v[116:119], v[158:159], off nt
	global_load_dwordx4 v[122:125], v[158:159], off offset:16 nt
	global_load_dwordx4 v[176:179], v[158:159], off offset:512 nt
	global_load_dwordx4 v[180:183], v[158:159], off offset:528 nt
	v_lshl_add_u64 v[126:127], v[126:127], 1, s[46:47]
	v_lshl_add_u64 v[156:157], s[28:29], 0, v[156:157]
	s_waitcnt vmcnt(3)
	v_pk_fma_f32 v[110:111], v[110:111], 0.5, v[118:119] op_sel_hi:[1,0,1]
	v_pk_fma_f32 v[108:109], v[108:109], 0.5, v[116:117] op_sel_hi:[1,0,1]
	s_waitcnt vmcnt(2)
	v_pk_fma_f32 v[106:107], v[106:107], 0.5, v[124:125] op_sel_hi:[1,0,1]
	v_pk_fma_f32 v[104:105], v[104:105], 0.5, v[122:123] op_sel_hi:[1,0,1]
	v_cvt_pk_bf16_f32 v116, v108, v109
	v_cvt_pk_bf16_f32 v117, v110, v111
	v_cvt_pk_bf16_f32 v118, v104, v105
	v_cvt_pk_bf16_f32 v119, v106, v107
	global_store_dwordx4 v[156:157], v[108:111], off nt
	global_store_dwordx4 v[156:157], v[104:107], off offset:16 nt
	global_store_dwordx4 v[126:127], v[116:119], off
	s_nop 1
	v_mul_f32_e32 v109, v109, v109
	v_mul_f32_e32 v111, v111, v111
	v_mul_f32_e32 v105, v105, v105
	v_mul_f32_e32 v107, v107, v107
	v_fmac_f32_e32 v109, v108, v108
	v_fmac_f32_e32 v111, v110, v110
	v_fmac_f32_e32 v105, v104, v104
	v_fmac_f32_e32 v107, v106, v106
	v_add_f32_e32 v104, v109, v111
	v_add_f32_e32 v105, v105, v107
	v_add_f32_e32 v108, v104, v105
	s_waitcnt vmcnt(4)
	v_pk_fma_f32 v[102:103], v[102:103], 0.5, v[178:179] op_sel_hi:[1,0,1]
	v_pk_fma_f32 v[100:101], v[100:101], 0.5, v[176:177] op_sel_hi:[1,0,1]
	s_waitcnt vmcnt(3)
	v_pk_fma_f32 v[106:107], v[98:99], 0.5, v[182:183] op_sel_hi:[1,0,1]
	v_pk_fma_f32 v[104:105], v[96:97], 0.5, v[180:181] op_sel_hi:[1,0,1]
	v_mul_f32_e32 v96, v101, v101
	v_mul_f32_e32 v97, v103, v103
	v_mul_f32_e32 v98, v105, v105
	v_mul_f32_e32 v99, v107, v107
	v_fmac_f32_e32 v96, v100, v100
	v_fmac_f32_e32 v97, v102, v102
	v_fmac_f32_e32 v98, v104, v104
	v_fmac_f32_e32 v99, v106, v106
	v_add_f32_e32 v96, v96, v97
	v_add_f32_e32 v97, v98, v99
	v_add_f32_e32 v96, v96, v97
	v_add_f32_e32 v96, v108, v96
	ds_bpermute_b32 v97, v120, v96
	global_store_dwordx4 v[156:157], v[100:103], off offset:512 nt
	global_store_dwordx4 v[156:157], v[104:107], off offset:528 nt
	v_cvt_pk_bf16_f32 v98, v100, v101
	v_cvt_pk_bf16_f32 v99, v102, v103
	v_cvt_pk_bf16_f32 v100, v104, v105
	s_waitcnt lgkmcnt(0)
	v_add_f32_e32 v96, v96, v97
	ds_bpermute_b32 v97, v114, v96
	v_cvt_pk_bf16_f32 v101, v106, v107
	global_store_dwordx4 v[126:127], v[98:101], off offset:256
	s_and_saveexec_b64 s[36:37], s[2:3]
	s_cbranch_execz .LBB0_590
	s_waitcnt lgkmcnt(0)
	v_add_f32_e32 v96, v96, v97
	v_mul_f32_e32 v96, 0x4b800000, v96
	v_trunc_f32_e32 v96, v96
	v_mul_f32_e32 v97, 0x2f800000, v96
	v_floor_f32_e32 v97, v97
	v_fmac_f32_e32 v96, 0xcf800000, v97
	v_cvt_u32_f32_e32 v96, v96
	v_cvt_u32_f32_e32 v97, v97
	v_lshl_add_u64 v[98:99], v[112:113], 3, s[18:19]
	global_atomic_add_x2 v[98:99], v[96:97], off
; __device__ __forceinline__ u32x4 pack8(const f32x4 a, const f32x4 b) { u32x4 w; w.x = cvt_pk_bf16(a[0], a[1]); w.y = cvt_pk_bf16(a[2], a[3]); w.z = cvt_pk_bf16(b[0], b[1]); w.w = cvt_pk_bf16(b[2], b[3]); return w; }
; __device__ __forceinline__ void ss_add(ssq_t* p, float sq) { __hip_atomic_fetch_add(p, (ssq_t)(sq * 16777216.0f), __ATOMIC_RELAXED, __HIP_MEMORY_SCOPE_AGENT); }
; __device__ __forceinline__ float dot4(const f32x4 a) { return (a[0] * a[0] + a[1] * a[1]) + (a[2] * a[2] + a[3] * a[3]); }
;     __device__ __forceinline__ void operator()(const f32x4 (&acc)[2][2][4][2], const Unit& u, int wr, int wc, int fr, int fq) const {
;     ...
;             for (int m = 0; m < 4; ++m) { const int row = row0 + ai * HALF + m * 16; const size_t off = (size_t)row * 2048 + col0; float sq = 0.f;
; #pragma unroll
;                 for (int bj = 0; bj < 2; ++bj) {
;                     const f32x4 x0 = __builtin_nontemporal_load((const f32x4*)(xin + off + bj * HALF)), x1 = __builtin_nontemporal_load((const f32x4*)(xin + off + bj * HALF + 4));
;                     const f32x4 v0 = x0 + acc[ai][bj][m][0] * alpha, v1 = x1 + acc[ai][bj][m][1] * alpha;
;                     __builtin_nontemporal_store(v0, (f32x4*)(xout + off + bj * HALF)); __builtin_nontemporal_store(v1, (f32x4*)(xout + off + bj * HALF + 4));
;                     if (WRITE_XB) *(u32x4*)(xb + off + bj * HALF) = pack8(v0, v1); sq += dot4(v0) + dot4(v1); }
;                 sq += __shfl_xor(sq, 16); sq += __shfl_xor(sq, 32);
;                 if (fq == 0) ss_add(ssout + row, sq); }
.LBB0_590:
	s_or_b64 exec, exec, s[36:37]
	v_or_b32_e32 v96, 32, v146
	s_waitcnt lgkmcnt(0)
	v_ashrrev_i32_e32 v97, 31, v96
	v_lshlrev_b64 v[98:99], 11, v[96:97]
	v_lshl_add_u64 v[106:107], v[98:99], 0, v[144:145]
	v_lshlrev_b64 v[108:109], 2, v[106:107]
	v_lshl_add_u64 v[110:111], s[52:53], 0, v[108:109]
	global_load_dwordx4 v[98:101], v[110:111], off nt
	global_load_dwordx4 v[102:105], v[110:111], off offset:16 nt
	global_load_dwordx4 v[176:179], v[110:111], off offset:512 nt
	global_load_dwordx4 v[180:183], v[110:111], off offset:528 nt
	v_lshl_add_u64 v[106:107], v[106:107], 1, s[46:47]
	v_lshl_add_u64 v[108:109], s[28:29], 0, v[108:109]
	s_waitcnt vmcnt(3)
	v_pk_fma_f32 v[94:95], v[94:95], 0.5, v[100:101] op_sel_hi:[1,0,1]
	v_pk_fma_f32 v[92:93], v[92:93], 0.5, v[98:99] op_sel_hi:[1,0,1]
	s_waitcnt vmcnt(2)
	v_pk_fma_f32 v[90:91], v[90:91], 0.5, v[104:105] op_sel_hi:[1,0,1]
	v_pk_fma_f32 v[88:89], v[88:89], 0.5, v[102:103] op_sel_hi:[1,0,1]
	v_cvt_pk_bf16_f32 v98, v92, v93
	v_cvt_pk_bf16_f32 v99, v94, v95
	v_cvt_pk_bf16_f32 v100, v88, v89
	v_cvt_pk_bf16_f32 v101, v90, v91
	global_store_dwordx4 v[108:109], v[92:95], off nt
	global_store_dwordx4 v[108:109], v[88:91], off offset:16 nt
	global_store_dwordx4 v[106:107], v[98:101], off
	s_nop 1
	v_mul_f32_e32 v93, v93, v93
	v_mul_f32_e32 v95, v95, v95
	v_mul_f32_e32 v89, v89, v89
	v_mul_f32_e32 v91, v91, v91
	v_fmac_f32_e32 v93, v92, v92
	v_fmac_f32_e32 v95, v94, v94
	v_fmac_f32_e32 v89, v88, v88
	v_fmac_f32_e32 v91, v90, v90
	v_add_f32_e32 v88, v93, v95
	v_add_f32_e32 v89, v89, v91
	v_add_f32_e32 v92, v88, v89
	s_waitcnt vmcnt(4)
	v_pk_fma_f32 v[86:87], v[86:87], 0.5, v[178:179] op_sel_hi:[1,0,1]
	v_pk_fma_f32 v[84:85], v[84:85], 0.5, v[176:177] op_sel_hi:[1,0,1]
	s_waitcnt vmcnt(3)
	v_pk_fma_f32 v[90:91], v[82:83], 0.5, v[182:183] op_sel_hi:[1,0,1]
	v_pk_fma_f32 v[88:89], v[80:81], 0.5, v[180:181] op_sel_hi:[1,0,1]
	v_mul_f32_e32 v80, v85, v85
	v_mul_f32_e32 v81, v87, v87
	v_mul_f32_e32 v82, v89, v89
	v_mul_f32_e32 v83, v91, v91
	v_fmac_f32_e32 v80, v84, v84
	v_fmac_f32_e32 v81, v86, v86
	v_fmac_f32_e32 v82, v88, v88
	v_fmac_f32_e32 v83, v90, v90
	v_add_f32_e32 v80, v80, v81
	v_add_f32_e32 v81, v82, v83
	v_add_f32_e32 v80, v80, v81
	v_add_f32_e32 v80, v92, v80
	ds_bpermute_b32 v81, v120, v80
	global_store_dwordx4 v[108:109], v[84:87], off offset:512 nt
	global_store_dwordx4 v[108:109], v[88:91], off offset:528 nt
	v_cvt_pk_bf16_f32 v82, v84, v85
	v_cvt_pk_bf16_f32 v83, v86, v87
	v_cvt_pk_bf16_f32 v84, v88, v89
	s_waitcnt lgkmcnt(0)
	v_add_f32_e32 v80, v80, v81
	ds_bpermute_b32 v81, v114, v80
	v_cvt_pk_bf16_f32 v85, v90, v91
	global_store_dwordx4 v[106:107], v[82:85], off offset:256
	s_and_saveexec_b64 s[36:37], s[2:3]
	s_cbranch_execz .LBB0_592
	s_waitcnt lgkmcnt(0)
	v_add_f32_e32 v80, v80, v81
	v_mul_f32_e32 v80, 0x4b800000, v80
	v_trunc_f32_e32 v80, v80
	v_mul_f32_e32 v81, 0x2f800000, v80
	v_floor_f32_e32 v81, v81
	v_fmac_f32_e32 v80, 0xcf800000, v81
	v_cvt_u32_f32_e32 v80, v80
	v_cvt_u32_f32_e32 v81, v81
	v_lshl_add_u64 v[82:83], v[96:97], 3, s[18:19]
	global_atomic_add_x2 v[82:83], v[80:81], off
.LBB0_592:
	s_or_b64 exec, exec, s[36:37]
	v_or_b32_e32 v80, 48, v146
	s_waitcnt lgkmcnt(0)
	v_ashrrev_i32_e32 v81, 31, v80
	v_lshlrev_b64 v[82:83], 11, v[80:81]
	v_lshl_add_u64 v[90:91], v[82:83], 0, v[144:145]
	v_lshlrev_b64 v[92:93], 2, v[90:91]
	v_lshl_add_u64 v[94:95], s[52:53], 0, v[92:93]
	global_load_dwordx4 v[82:85], v[94:95], off nt
	global_load_dwordx4 v[86:89], v[94:95], off offset:16 nt
	global_load_dwordx4 v[176:179], v[94:95], off offset:512 nt
	global_load_dwordx4 v[180:183], v[94:95], off offset:528 nt
	v_lshl_add_u64 v[90:91], v[90:91], 1, s[46:47]
	v_lshl_add_u64 v[92:93], s[28:29], 0, v[92:93]
	s_waitcnt vmcnt(3)
	v_pk_fma_f32 v[78:79], v[78:79], 0.5, v[84:85] op_sel_hi:[1,0,1]
	v_pk_fma_f32 v[76:77], v[76:77], 0.5, v[82:83] op_sel_hi:[1,0,1]
	s_waitcnt vmcnt(2)
	v_pk_fma_f32 v[74:75], v[74:75], 0.5, v[88:89] op_sel_hi:[1,0,1]
	v_pk_fma_f32 v[72:73], v[72:73], 0.5, v[86:87] op_sel_hi:[1,0,1]
	v_cvt_pk_bf16_f32 v82, v76, v77
	v_cvt_pk_bf16_f32 v83, v78, v79
	v_cvt_pk_bf16_f32 v84, v72, v73
	v_cvt_pk_bf16_f32 v85, v74, v75
	global_store_dwordx4 v[92:93], v[76:79], off nt
	global_store_dwordx4 v[92:93], v[72:75], off offset:16 nt
	global_store_dwordx4 v[90:91], v[82:85], off
	s_nop 1
	v_mul_f32_e32 v77, v77, v77
	v_mul_f32_e32 v79, v79, v79
	v_mul_f32_e32 v73, v73, v73
	v_mul_f32_e32 v75, v75, v75
	v_fmac_f32_e32 v77, v76, v76
	v_fmac_f32_e32 v79, v78, v78
	v_fmac_f32_e32 v73, v72, v72
	v_fmac_f32_e32 v75, v74, v74
	v_add_f32_e32 v72, v77, v79
	v_add_f32_e32 v73, v73, v75
	v_add_f32_e32 v76, v72, v73
	s_waitcnt vmcnt(4)
	v_pk_fma_f32 v[70:71], v[70:71], 0.5, v[178:179] op_sel_hi:[1,0,1]
	v_pk_fma_f32 v[68:69], v[68:69], 0.5, v[176:177] op_sel_hi:[1,0,1]
	s_waitcnt vmcnt(3)
	v_pk_fma_f32 v[74:75], v[66:67], 0.5, v[182:183] op_sel_hi:[1,0,1]
	v_pk_fma_f32 v[72:73], v[64:65], 0.5, v[180:181] op_sel_hi:[1,0,1]
	v_mul_f32_e32 v64, v69, v69
	v_mul_f32_e32 v65, v71, v71
	v_mul_f32_e32 v66, v73, v73
	v_mul_f32_e32 v67, v75, v75
	v_fmac_f32_e32 v64, v68, v68
	v_fmac_f32_e32 v65, v70, v70
	v_fmac_f32_e32 v66, v72, v72
	v_fmac_f32_e32 v67, v74, v74
	v_add_f32_e32 v64, v64, v65
	v_add_f32_e32 v65, v66, v67
	v_add_f32_e32 v64, v64, v65
	v_add_f32_e32 v64, v76, v64
	ds_bpermute_b32 v65, v120, v64
	global_store_dwordx4 v[92:93], v[68:71], off offset:512 nt
	global_store_dwordx4 v[92:93], v[72:75], off offset:528 nt
	v_cvt_pk_bf16_f32 v66, v68, v69
	v_cvt_pk_bf16_f32 v67, v70, v71
	v_cvt_pk_bf16_f32 v68, v72, v73
	s_waitcnt lgkmcnt(0)
	v_add_f32_e32 v64, v64, v65
	ds_bpermute_b32 v65, v114, v64
	v_cvt_pk_bf16_f32 v69, v74, v75
	global_store_dwordx4 v[90:91], v[66:69], off offset:256
	s_and_saveexec_b64 s[36:37], s[2:3]
	s_cbranch_execz .LBB0_594
	s_waitcnt lgkmcnt(0)
	v_add_f32_e32 v64, v64, v65
	v_mul_f32_e32 v64, 0x4b800000, v64
	v_trunc_f32_e32 v64, v64
	v_mul_f32_e32 v65, 0x2f800000, v64
	v_floor_f32_e32 v65, v65
	v_fmac_f32_e32 v64, 0xcf800000, v65
	v_cvt_u32_f32_e32 v64, v64
	v_cvt_u32_f32_e32 v65, v65
	v_lshl_add_u64 v[66:67], v[80:81], 3, s[18:19]
	global_atomic_add_x2 v[66:67], v[64:65], off
; __device__ __forceinline__ u32x4 pack8(const f32x4 a, const f32x4 b) { u32x4 w; w.x = cvt_pk_bf16(a[0], a[1]); w.y = cvt_pk_bf16(a[2], a[3]); w.z = cvt_pk_bf16(b[0], b[1]); w.w = cvt_pk_bf16(b[2], b[3]); return w; }
; __device__ __forceinline__ void ss_add(ssq_t* p, float sq) { __hip_atomic_fetch_add(p, (ssq_t)(sq * 16777216.0f), __ATOMIC_RELAXED, __HIP_MEMORY_SCOPE_AGENT); }
; __device__ __forceinline__ float dot4(const f32x4 a) { return (a[0] * a[0] + a[1] * a[1]) + (a[2] * a[2] + a[3] * a[3]); }
;     __device__ __forceinline__ void operator()(const f32x4 (&acc)[2][2][4][2], const Unit& u, int wr, int wc, int fr, int fq) const {
;     ...
;             for (int m = 0; m < 4; ++m) { const int row = row0 + ai * HALF + m * 16; const size_t off = (size_t)row * 2048 + col0; float sq = 0.f;
; #pragma unroll
;                 for (int bj = 0; bj < 2; ++bj) {
;                     const f32x4 x0 = __builtin_nontemporal_load((const f32x4*)(xin + off + bj * HALF)), x1 = __builtin_nontemporal_load((const f32x4*)(xin + off + bj * HALF + 4));
;                     const f32x4 v0 = x0 + acc[ai][bj][m][0] * alpha, v1 = x1 + acc[ai][bj][m][1] * alpha;
;                     __builtin_nontemporal_store(v0, (f32x4*)(xout + off + bj * HALF)); __builtin_nontemporal_store(v1, (f32x4*)(xout + off + bj * HALF + 4));
;                     if (WRITE_XB) *(u32x4*)(xb + off + bj * HALF) = pack8(v0, v1); sq += dot4(v0) + dot4(v1); }
;                 sq += __shfl_xor(sq, 16); sq += __shfl_xor(sq, 32);
;                 if (fq == 0) ss_add(ssout + row, sq); }
.LBB0_594:
	s_or_b64 exec, exec, s[36:37]
	v_add_u32_e32 v64, 0x80, v146
	s_waitcnt lgkmcnt(0)
	v_ashrrev_i32_e32 v65, 31, v64
	v_lshlrev_b64 v[66:67], 11, v[64:65]
	v_lshl_add_u64 v[74:75], v[66:67], 0, v[144:145]
	v_lshlrev_b64 v[76:77], 2, v[74:75]
	v_lshl_add_u64 v[78:79], s[52:53], 0, v[76:77]
	global_load_dwordx4 v[66:69], v[78:79], off nt
	global_load_dwordx4 v[70:73], v[78:79], off offset:16 nt
	global_load_dwordx4 v[176:179], v[78:79], off offset:512 nt
	global_load_dwordx4 v[180:183], v[78:79], off offset:528 nt
	v_lshl_add_u64 v[74:75], v[74:75], 1, s[46:47]
	v_lshl_add_u64 v[76:77], s[28:29], 0, v[76:77]
	s_waitcnt vmcnt(3)
	v_pk_fma_f32 v[62:63], v[62:63], 0.5, v[68:69] op_sel_hi:[1,0,1]
	v_pk_fma_f32 v[60:61], v[60:61], 0.5, v[66:67] op_sel_hi:[1,0,1]
	s_waitcnt vmcnt(2)
	v_pk_fma_f32 v[58:59], v[58:59], 0.5, v[72:73] op_sel_hi:[1,0,1]
	v_pk_fma_f32 v[56:57], v[56:57], 0.5, v[70:71] op_sel_hi:[1,0,1]
	v_cvt_pk_bf16_f32 v66, v60, v61
	v_cvt_pk_bf16_f32 v67, v62, v63
	v_cvt_pk_bf16_f32 v68, v56, v57
	v_cvt_pk_bf16_f32 v69, v58, v59
	global_store_dwordx4 v[76:77], v[60:63], off nt
	global_store_dwordx4 v[76:77], v[56:59], off offset:16 nt
	global_store_dwordx4 v[74:75], v[66:69], off
	s_nop 1
	v_mul_f32_e32 v61, v61, v61
	v_mul_f32_e32 v63, v63, v63
	v_mul_f32_e32 v57, v57, v57
	v_mul_f32_e32 v59, v59, v59
	v_fmac_f32_e32 v61, v60, v60
	v_fmac_f32_e32 v63, v62, v62
	v_fmac_f32_e32 v57, v56, v56
	v_fmac_f32_e32 v59, v58, v58
	v_add_f32_e32 v56, v61, v63
	v_add_f32_e32 v57, v57, v59
	v_add_f32_e32 v60, v56, v57
	s_waitcnt vmcnt(4)
	v_pk_fma_f32 v[54:55], v[54:55], 0.5, v[178:179] op_sel_hi:[1,0,1]
	v_pk_fma_f32 v[52:53], v[52:53], 0.5, v[176:177] op_sel_hi:[1,0,1]
	s_waitcnt vmcnt(3)
	v_pk_fma_f32 v[58:59], v[50:51], 0.5, v[182:183] op_sel_hi:[1,0,1]
	v_pk_fma_f32 v[56:57], v[48:49], 0.5, v[180:181] op_sel_hi:[1,0,1]
	v_mul_f32_e32 v48, v53, v53
	v_mul_f32_e32 v49, v55, v55
	v_mul_f32_e32 v50, v57, v57
	v_mul_f32_e32 v51, v59, v59
	v_fmac_f32_e32 v48, v52, v52
	v_fmac_f32_e32 v49, v54, v54
	v_fmac_f32_e32 v50, v56, v56
	v_fmac_f32_e32 v51, v58, v58
	v_add_f32_e32 v48, v48, v49
	v_add_f32_e32 v49, v50, v51
	v_add_f32_e32 v48, v48, v49
	v_add_f32_e32 v48, v60, v48
	ds_bpermute_b32 v49, v120, v48
	global_store_dwordx4 v[76:77], v[52:55], off offset:512 nt
	global_store_dwordx4 v[76:77], v[56:59], off offset:528 nt
	v_cvt_pk_bf16_f32 v50, v52, v53
	v_cvt_pk_bf16_f32 v51, v54, v55
	v_cvt_pk_bf16_f32 v52, v56, v57
	s_waitcnt lgkmcnt(0)
	v_add_f32_e32 v48, v48, v49
	ds_bpermute_b32 v49, v114, v48
	v_cvt_pk_bf16_f32 v53, v58, v59
	global_store_dwordx4 v[74:75], v[50:53], off offset:256
	s_and_saveexec_b64 s[36:37], s[2:3]
	s_cbranch_execz .LBB0_596
	s_waitcnt lgkmcnt(0)
	v_add_f32_e32 v48, v48, v49
	v_mul_f32_e32 v48, 0x4b800000, v48
	v_trunc_f32_e32 v48, v48
	v_mul_f32_e32 v49, 0x2f800000, v48
	v_floor_f32_e32 v49, v49
	v_fmac_f32_e32 v48, 0xcf800000, v49
	v_cvt_u32_f32_e32 v48, v48
	v_cvt_u32_f32_e32 v49, v49
	v_lshl_add_u64 v[50:51], v[64:65], 3, s[18:19]
	global_atomic_add_x2 v[50:51], v[48:49], off
.LBB0_596:
	s_or_b64 exec, exec, s[36:37]
	v_add_u32_e32 v48, 0x90, v146
	s_waitcnt lgkmcnt(0)
	v_ashrrev_i32_e32 v49, 31, v48
	v_lshlrev_b64 v[50:51], 11, v[48:49]
	v_lshl_add_u64 v[58:59], v[50:51], 0, v[144:145]
	v_lshlrev_b64 v[60:61], 2, v[58:59]
	v_lshl_add_u64 v[62:63], s[52:53], 0, v[60:61]
	global_load_dwordx4 v[50:53], v[62:63], off nt
	global_load_dwordx4 v[54:57], v[62:63], off offset:16 nt
	global_load_dwordx4 v[176:179], v[62:63], off offset:512 nt
	global_load_dwordx4 v[180:183], v[62:63], off offset:528 nt
	v_lshl_add_u64 v[58:59], v[58:59], 1, s[46:47]
	v_lshl_add_u64 v[60:61], s[28:29], 0, v[60:61]
	s_waitcnt vmcnt(3)
	v_pk_fma_f32 v[46:47], v[46:47], 0.5, v[52:53] op_sel_hi:[1,0,1]
	v_pk_fma_f32 v[44:45], v[44:45], 0.5, v[50:51] op_sel_hi:[1,0,1]
	s_waitcnt vmcnt(2)
	v_pk_fma_f32 v[42:43], v[42:43], 0.5, v[56:57] op_sel_hi:[1,0,1]
	v_pk_fma_f32 v[40:41], v[40:41], 0.5, v[54:55] op_sel_hi:[1,0,1]
	v_cvt_pk_bf16_f32 v50, v44, v45
	v_cvt_pk_bf16_f32 v51, v46, v47
	v_cvt_pk_bf16_f32 v52, v40, v41
	v_cvt_pk_bf16_f32 v53, v42, v43
	global_store_dwordx4 v[60:61], v[44:47], off nt
	global_store_dwordx4 v[60:61], v[40:43], off offset:16 nt
	global_store_dwordx4 v[58:59], v[50:53], off
	s_nop 1
	v_mul_f32_e32 v45, v45, v45
	v_mul_f32_e32 v47, v47, v47
	v_mul_f32_e32 v41, v41, v41
	v_mul_f32_e32 v43, v43, v43
	v_fmac_f32_e32 v45, v44, v44
	v_fmac_f32_e32 v47, v46, v46
	v_fmac_f32_e32 v41, v40, v40
	v_fmac_f32_e32 v43, v42, v42
	v_add_f32_e32 v40, v45, v47
	v_add_f32_e32 v41, v41, v43
	v_add_f32_e32 v44, v40, v41
	s_waitcnt vmcnt(4)
	v_pk_fma_f32 v[38:39], v[38:39], 0.5, v[178:179] op_sel_hi:[1,0,1]
	v_pk_fma_f32 v[36:37], v[36:37], 0.5, v[176:177] op_sel_hi:[1,0,1]
	s_waitcnt vmcnt(3)
	v_pk_fma_f32 v[42:43], v[34:35], 0.5, v[182:183] op_sel_hi:[1,0,1]
	v_pk_fma_f32 v[40:41], v[32:33], 0.5, v[180:181] op_sel_hi:[1,0,1]
	v_mul_f32_e32 v32, v37, v37
	v_mul_f32_e32 v33, v39, v39
	v_mul_f32_e32 v34, v41, v41
	v_mul_f32_e32 v35, v43, v43
	v_fmac_f32_e32 v32, v36, v36
	v_fmac_f32_e32 v33, v38, v38
	v_fmac_f32_e32 v34, v40, v40
	v_fmac_f32_e32 v35, v42, v42
	v_add_f32_e32 v32, v32, v33
	v_add_f32_e32 v33, v34, v35
	v_add_f32_e32 v32, v32, v33
	v_add_f32_e32 v32, v44, v32
	ds_bpermute_b32 v33, v120, v32
	global_store_dwordx4 v[60:61], v[36:39], off offset:512 nt
	global_store_dwordx4 v[60:61], v[40:43], off offset:528 nt
	v_cvt_pk_bf16_f32 v34, v36, v37
	v_cvt_pk_bf16_f32 v35, v38, v39
	v_cvt_pk_bf16_f32 v36, v40, v41
	s_waitcnt lgkmcnt(0)
	v_add_f32_e32 v32, v32, v33
	ds_bpermute_b32 v33, v114, v32
	v_cvt_pk_bf16_f32 v37, v42, v43
	global_store_dwordx4 v[58:59], v[34:37], off offset:256
	s_and_saveexec_b64 s[36:37], s[2:3]
	s_cbranch_execz .LBB0_598
	s_waitcnt lgkmcnt(0)
	v_add_f32_e32 v32, v32, v33
	v_mul_f32_e32 v32, 0x4b800000, v32
	v_trunc_f32_e32 v32, v32
	v_mul_f32_e32 v33, 0x2f800000, v32
	v_floor_f32_e32 v33, v33
	v_fmac_f32_e32 v32, 0xcf800000, v33
	v_cvt_u32_f32_e32 v32, v32
	v_cvt_u32_f32_e32 v33, v33
	v_lshl_add_u64 v[34:35], v[48:49], 3, s[18:19]
	global_atomic_add_x2 v[34:35], v[32:33], off
; __device__ __forceinline__ u32x4 pack8(const f32x4 a, const f32x4 b) { u32x4 w; w.x = cvt_pk_bf16(a[0], a[1]); w.y = cvt_pk_bf16(a[2], a[3]); w.z = cvt_pk_bf16(b[0], b[1]); w.w = cvt_pk_bf16(b[2], b[3]); return w; }
; __device__ __forceinline__ void ss_add(ssq_t* p, float sq) { __hip_atomic_fetch_add(p, (ssq_t)(sq * 16777216.0f), __ATOMIC_RELAXED, __HIP_MEMORY_SCOPE_AGENT); }
; __device__ __forceinline__ float dot4(const f32x4 a) { return (a[0] * a[0] + a[1] * a[1]) + (a[2] * a[2] + a[3] * a[3]); }
;     __device__ __forceinline__ void operator()(const f32x4 (&acc)[2][2][4][2], const Unit& u, int wr, int wc, int fr, int fq) const {
;     ...
;             for (int m = 0; m < 4; ++m) { const int row = row0 + ai * HALF + m * 16; const size_t off = (size_t)row * 2048 + col0; float sq = 0.f;
; #pragma unroll
;                 for (int bj = 0; bj < 2; ++bj) {
;                     const f32x4 x0 = __builtin_nontemporal_load((const f32x4*)(xin + off + bj * HALF)), x1 = __builtin_nontemporal_load((const f32x4*)(xin + off + bj * HALF + 4));
;                     const f32x4 v0 = x0 + acc[ai][bj][m][0] * alpha, v1 = x1 + acc[ai][bj][m][1] * alpha;
;                     __builtin_nontemporal_store(v0, (f32x4*)(xout + off + bj * HALF)); __builtin_nontemporal_store(v1, (f32x4*)(xout + off + bj * HALF + 4));
;                     if (WRITE_XB) *(u32x4*)(xb + off + bj * HALF) = pack8(v0, v1); sq += dot4(v0) + dot4(v1); }
;                 sq += __shfl_xor(sq, 16); sq += __shfl_xor(sq, 32);
;                 if (fq == 0) ss_add(ssout + row, sq); }
.LBB0_598:
	s_or_b64 exec, exec, s[36:37]
	v_add_u32_e32 v32, 0xa0, v146
	s_waitcnt lgkmcnt(0)
	v_ashrrev_i32_e32 v33, 31, v32
	v_lshlrev_b64 v[34:35], 11, v[32:33]
	v_lshl_add_u64 v[42:43], v[34:35], 0, v[144:145]
	v_lshlrev_b64 v[44:45], 2, v[42:43]
	v_lshl_add_u64 v[46:47], s[52:53], 0, v[44:45]
	global_load_dwordx4 v[34:37], v[46:47], off nt
	global_load_dwordx4 v[38:41], v[46:47], off offset:16 nt
	global_load_dwordx4 v[176:179], v[46:47], off offset:512 nt
	global_load_dwordx4 v[180:183], v[46:47], off offset:528 nt
	v_lshl_add_u64 v[42:43], v[42:43], 1, s[46:47]
	v_lshl_add_u64 v[44:45], s[28:29], 0, v[44:45]
	s_waitcnt vmcnt(3)
	v_pk_fma_f32 v[30:31], v[30:31], 0.5, v[36:37] op_sel_hi:[1,0,1]
	v_pk_fma_f32 v[28:29], v[28:29], 0.5, v[34:35] op_sel_hi:[1,0,1]
	s_waitcnt vmcnt(2)
	v_pk_fma_f32 v[26:27], v[26:27], 0.5, v[40:41] op_sel_hi:[1,0,1]
	v_pk_fma_f32 v[24:25], v[24:25], 0.5, v[38:39] op_sel_hi:[1,0,1]
	v_cvt_pk_bf16_f32 v34, v28, v29
	v_cvt_pk_bf16_f32 v35, v30, v31
	v_cvt_pk_bf16_f32 v36, v24, v25
	v_cvt_pk_bf16_f32 v37, v26, v27
	global_store_dwordx4 v[44:45], v[28:31], off nt
	global_store_dwordx4 v[44:45], v[24:27], off offset:16 nt
	global_store_dwordx4 v[42:43], v[34:37], off
	s_nop 1
	v_mul_f32_e32 v29, v29, v29
	v_mul_f32_e32 v31, v31, v31
	v_mul_f32_e32 v25, v25, v25
	v_mul_f32_e32 v27, v27, v27
	v_fmac_f32_e32 v29, v28, v28
	v_fmac_f32_e32 v31, v30, v30
	v_fmac_f32_e32 v25, v24, v24
	v_fmac_f32_e32 v27, v26, v26
	v_add_f32_e32 v24, v29, v31
	v_add_f32_e32 v25, v25, v27
	v_add_f32_e32 v28, v24, v25
	s_waitcnt vmcnt(4)
	v_pk_fma_f32 v[22:23], v[22:23], 0.5, v[178:179] op_sel_hi:[1,0,1]
	v_pk_fma_f32 v[20:21], v[20:21], 0.5, v[176:177] op_sel_hi:[1,0,1]
	s_waitcnt vmcnt(3)
	v_pk_fma_f32 v[26:27], v[18:19], 0.5, v[182:183] op_sel_hi:[1,0,1]
	v_pk_fma_f32 v[24:25], v[16:17], 0.5, v[180:181] op_sel_hi:[1,0,1]
	v_mul_f32_e32 v16, v21, v21
	v_mul_f32_e32 v17, v23, v23
	v_mul_f32_e32 v18, v25, v25
	v_mul_f32_e32 v19, v27, v27
	v_fmac_f32_e32 v16, v20, v20
	v_fmac_f32_e32 v17, v22, v22
	v_fmac_f32_e32 v18, v24, v24
	v_fmac_f32_e32 v19, v26, v26
	v_add_f32_e32 v16, v16, v17
	v_add_f32_e32 v17, v18, v19
	v_add_f32_e32 v16, v16, v17
	v_add_f32_e32 v16, v28, v16
	ds_bpermute_b32 v17, v120, v16
	global_store_dwordx4 v[44:45], v[20:23], off offset:512 nt
	global_store_dwordx4 v[44:45], v[24:27], off offset:528 nt
	v_cvt_pk_bf16_f32 v18, v20, v21
	v_cvt_pk_bf16_f32 v19, v22, v23
	v_cvt_pk_bf16_f32 v20, v24, v25
	s_waitcnt lgkmcnt(0)
	v_add_f32_e32 v16, v16, v17
	ds_bpermute_b32 v17, v114, v16
	v_cvt_pk_bf16_f32 v21, v26, v27
	global_store_dwordx4 v[42:43], v[18:21], off offset:256
	s_and_saveexec_b64 s[36:37], s[2:3]
	s_cbranch_execz .LBB0_600
	s_waitcnt lgkmcnt(0)
	v_add_f32_e32 v16, v16, v17
	v_mul_f32_e32 v16, 0x4b800000, v16
	v_trunc_f32_e32 v16, v16
	v_mul_f32_e32 v17, 0x2f800000, v16
	v_floor_f32_e32 v17, v17
	v_fmac_f32_e32 v16, 0xcf800000, v17
	v_cvt_u32_f32_e32 v16, v16
	v_cvt_u32_f32_e32 v17, v17
	v_lshl_add_u64 v[18:19], v[32:33], 3, s[18:19]
	global_atomic_add_x2 v[18:19], v[16:17], off
.LBB0_600:
	s_or_b64 exec, exec, s[36:37]
	v_add_u32_e32 v16, 0xb0, v146
	s_waitcnt lgkmcnt(0)
	v_ashrrev_i32_e32 v17, 31, v16
	v_lshlrev_b64 v[18:19], 11, v[16:17]
	v_lshl_add_u64 v[26:27], v[18:19], 0, v[144:145]
	v_lshlrev_b64 v[28:29], 2, v[26:27]
	v_lshl_add_u64 v[30:31], s[52:53], 0, v[28:29]
	global_load_dwordx4 v[18:21], v[30:31], off nt
	global_load_dwordx4 v[22:25], v[30:31], off offset:16 nt
	global_load_dwordx4 v[176:179], v[30:31], off offset:512 nt
	global_load_dwordx4 v[180:183], v[30:31], off offset:528 nt
	v_lshl_add_u64 v[26:27], v[26:27], 1, s[46:47]
	v_lshl_add_u64 v[28:29], s[28:29], 0, v[28:29]
	s_waitcnt vmcnt(3)
	v_pk_fma_f32 v[14:15], v[14:15], 0.5, v[20:21] op_sel_hi:[1,0,1]
	v_pk_fma_f32 v[12:13], v[12:13], 0.5, v[18:19] op_sel_hi:[1,0,1]
	s_waitcnt vmcnt(2)
	v_pk_fma_f32 v[10:11], v[10:11], 0.5, v[24:25] op_sel_hi:[1,0,1]
	v_pk_fma_f32 v[8:9], v[8:9], 0.5, v[22:23] op_sel_hi:[1,0,1]
	v_cvt_pk_bf16_f32 v18, v12, v13
	v_cvt_pk_bf16_f32 v19, v14, v15
	v_cvt_pk_bf16_f32 v20, v8, v9
	v_cvt_pk_bf16_f32 v21, v10, v11
	global_store_dwordx4 v[28:29], v[12:15], off nt
	global_store_dwordx4 v[28:29], v[8:11], off offset:16 nt
	global_store_dwordx4 v[26:27], v[18:21], off
	s_nop 1
	v_mul_f32_e32 v13, v13, v13
	v_mul_f32_e32 v15, v15, v15
	v_mul_f32_e32 v9, v9, v9
	v_mul_f32_e32 v11, v11, v11
	v_fmac_f32_e32 v13, v12, v12
	v_fmac_f32_e32 v15, v14, v14
	v_fmac_f32_e32 v9, v8, v8
	v_fmac_f32_e32 v11, v10, v10
	v_add_f32_e32 v8, v13, v15
	v_add_f32_e32 v9, v9, v11
	v_add_f32_e32 v12, v8, v9
	s_waitcnt vmcnt(4)
	v_pk_fma_f32 v[6:7], v[6:7], 0.5, v[178:179] op_sel_hi:[1,0,1]
	v_pk_fma_f32 v[4:5], v[4:5], 0.5, v[176:177] op_sel_hi:[1,0,1]
	s_waitcnt vmcnt(3)
	v_pk_fma_f32 v[10:11], v[2:3], 0.5, v[182:183] op_sel_hi:[1,0,1]
	v_pk_fma_f32 v[8:9], v[0:1], 0.5, v[180:181] op_sel_hi:[1,0,1]
	v_mul_f32_e32 v0, v5, v5
	v_mul_f32_e32 v1, v7, v7
	v_mul_f32_e32 v2, v9, v9
	v_mul_f32_e32 v3, v11, v11
	v_fmac_f32_e32 v0, v4, v4
	v_fmac_f32_e32 v1, v6, v6
	v_fmac_f32_e32 v2, v8, v8
	v_fmac_f32_e32 v3, v10, v10
	v_add_f32_e32 v0, v0, v1
	v_add_f32_e32 v1, v2, v3
	v_add_f32_e32 v0, v0, v1
	v_add_f32_e32 v0, v12, v0
	ds_bpermute_b32 v1, v120, v0
	global_store_dwordx4 v[28:29], v[4:7], off offset:512 nt
	global_store_dwordx4 v[28:29], v[8:11], off offset:528 nt
	v_cvt_pk_bf16_f32 v2, v4, v5
	v_cvt_pk_bf16_f32 v3, v6, v7
	v_cvt_pk_bf16_f32 v4, v8, v9
	s_waitcnt lgkmcnt(0)
	v_add_f32_e32 v0, v0, v1
	ds_bpermute_b32 v1, v114, v0
	v_cvt_pk_bf16_f32 v5, v10, v11
	global_store_dwordx4 v[26:27], v[2:5], off offset:256
	s_and_saveexec_b64 s[36:37], s[2:3]
	s_cbranch_execz .LBB0_602
	s_waitcnt lgkmcnt(0)
	v_add_f32_e32 v0, v0, v1
	v_mul_f32_e32 v0, 0x4b800000, v0
	v_trunc_f32_e32 v0, v0
	v_mul_f32_e32 v1, 0x2f800000, v0
	v_floor_f32_e32 v1, v1
	v_fmac_f32_e32 v0, 0xcf800000, v1
	v_cvt_u32_f32_e32 v0, v0
	v_cvt_u32_f32_e32 v1, v1
	v_lshl_add_u64 v[2:3], v[16:17], 3, s[18:19]
	global_atomic_add_x2 v[2:3], v[0:1], off

; __device__ __forceinline__ u32x4 pack8(const f32x4 a, const f32x4 b) { u32x4 w; w.x = cvt_pk_bf16(a[0], a[1]); w.y = cvt_pk_bf16(a[2], a[3]); w.z = cvt_pk_bf16(b[0], b[1]); w.w = cvt_pk_bf16(b[2], b[3]); return w; }
; __device__ __forceinline__ void ss_add(ssq_t* p, float sq) { __hip_atomic_fetch_add(p, (ssq_t)(sq * 16777216.0f), __ATOMIC_RELAXED, __HIP_MEMORY_SCOPE_AGENT); }
; __device__ __forceinline__ float dot4(const f32x4 a) { return (a[0] * a[0] + a[1] * a[1]) + (a[2] * a[2] + a[3] * a[3]); }
;     __device__ __forceinline__ void operator()(const f32x4 (&acc)[2][2][4][2], const Unit& u, int wr, int wc, int fr, int fq) const {
;     ...
;             for (int m = 0; m < 4; ++m) { const int row = row0 + ai * HALF + m * 16; const size_t off = (size_t)row * 2048 + col0; float sq = 0.f;
; #pragma unroll
;                 for (int bj = 0; bj < 2; ++bj) {
;                     const f32x4 x0 = __builtin_nontemporal_load((const f32x4*)(xin + off + bj * HALF)), x1 = __builtin_nontemporal_load((const f32x4*)(xin + off + bj * HALF + 4));
;                     const f32x4 v0 = x0 + acc[ai][bj][m][0] * alpha, v1 = x1 + acc[ai][bj][m][1] * alpha;
;                     __builtin_nontemporal_store(v0, (f32x4*)(xout + off + bj * HALF)); __builtin_nontemporal_store(v1, (f32x4*)(xout + off + bj * HALF + 4));
;                     if (WRITE_XB) *(u32x4*)(xb + off + bj * HALF) = pack8(v0, v1); sq += dot4(v0) + dot4(v1); }
;                 sq += __shfl_xor(sq, 16); sq += __shfl_xor(sq, 32);
;                 if (fq == 0) ss_add(ssout + row, sq); }
.LBB0_1306:
	v_lshl_add_u32 v146, s62, 8, v148
	v_lshl_add_u32 v144, s64, 8, v150
	v_ashrrev_i32_e32 v147, 31, v146
	v_ashrrev_i32_e32 v145, 31, v144
	v_lshlrev_b64 v[156:157], 11, v[146:147]
	v_lshl_add_u64 v[164:165], v[156:157], 0, v[144:145]
	v_lshl_add_u64 v[168:169], v[164:165], 2, s[28:29]
	global_load_dwordx4 v[156:159], v[168:169], off nt
	global_load_dwordx4 v[160:163], v[168:169], off offset:16 nt
	global_load_dwordx4 v[176:179], v[168:169], off offset:512 nt
	global_load_dwordx4 v[180:183], v[168:169], off offset:528 nt
	v_lshl_add_u64 v[170:171], v[164:165], 1, s[46:47]
	s_waitcnt vmcnt(2)
	v_pk_add_f32 v[126:127], v[126:127], v[158:159]
	v_pk_add_f32 v[124:125], v[124:125], v[156:157]
	v_pk_add_f32 v[158:159], v[122:123], v[162:163]
	v_pk_add_f32 v[156:157], v[120:121], v[160:161]
	v_cvt_pk_bf16_f32 v120, v124, v125
	v_cvt_pk_bf16_f32 v121, v126, v127
	v_cvt_pk_bf16_f32 v122, v156, v157
	v_cvt_pk_bf16_f32 v123, v158, v159
	global_store_dwordx4 v[168:169], v[124:127], off nt
	global_store_dwordx4 v[168:169], v[156:159], off offset:16 nt
	global_store_dwordx4 v[170:171], v[120:123], off
	s_nop 1
	v_and_b32_e32 v121, 64, v154
	v_xor_b32_e32 v120, 16, v154
	v_add_u32_e32 v121, 64, v121
	v_xor_b32_e32 v122, 32, v154
	v_cmp_lt_i32_e32 vcc, v120, v121
	v_mul_f32_e32 v123, v127, v127
	v_mul_f32_e32 v127, v159, v159
	v_cndmask_b32_e32 v120, v154, v120, vcc
	v_cmp_lt_i32_e32 vcc, v122, v121
	v_fmac_f32_e32 v123, v126, v126
	v_fmac_f32_e32 v127, v158, v158
	v_cndmask_b32_e32 v121, v154, v122, vcc
	v_mul_f32_e32 v122, v125, v125
	v_mul_f32_e32 v125, v157, v157
	v_fmac_f32_e32 v122, v124, v124
	v_fmac_f32_e32 v125, v156, v156
	v_add_f32_e32 v122, v122, v123
	v_add_f32_e32 v123, v125, v127
	v_add_f32_e32 v126, v122, v123
	v_lshlrev_b32_e32 v120, 2, v120
	s_waitcnt vmcnt(4)
	v_pk_add_f32 v[118:119], v[118:119], v[178:179]
	v_pk_add_f32 v[116:117], v[116:117], v[176:177]
	s_waitcnt vmcnt(3)
	v_pk_add_f32 v[124:125], v[114:115], v[182:183]
	v_pk_add_f32 v[122:123], v[112:113], v[180:181]
	v_mul_f32_e32 v112, v117, v117
	v_mul_f32_e32 v113, v119, v119
	v_mul_f32_e32 v114, v123, v123
	v_mul_f32_e32 v115, v125, v125
	v_fmac_f32_e32 v112, v116, v116
	v_fmac_f32_e32 v113, v118, v118
	v_fmac_f32_e32 v114, v122, v122
	v_fmac_f32_e32 v115, v124, v124
	v_add_f32_e32 v112, v112, v113
	v_add_f32_e32 v113, v114, v115
	v_add_f32_e32 v112, v112, v113
	v_add_f32_e32 v112, v126, v112
	ds_bpermute_b32 v113, v120, v112
	v_lshlrev_b32_e32 v114, 2, v121
	global_store_dwordx4 v[168:169], v[116:119], off offset:512 nt
	global_store_dwordx4 v[168:169], v[122:125], off offset:528 nt
	s_waitcnt lgkmcnt(0)
	v_add_f32_e32 v112, v112, v113
	ds_bpermute_b32 v113, v114, v112
	v_cvt_pk_bf16_f32 v116, v116, v117
	v_cvt_pk_bf16_f32 v117, v118, v119
	v_cvt_pk_bf16_f32 v118, v122, v123
	v_cvt_pk_bf16_f32 v119, v124, v125
	global_store_dwordx4 v[170:171], v[116:119], off offset:256
	s_and_saveexec_b64 s[48:49], s[2:3]
	s_cbranch_execz .LBB0_1308
	s_waitcnt lgkmcnt(0)
	v_add_f32_e32 v112, v112, v113
	v_mul_f32_e32 v112, 0x4b800000, v112
	v_trunc_f32_e32 v112, v112
	v_mul_f32_e32 v113, 0x2f800000, v112
	v_floor_f32_e32 v113, v113
	v_fmac_f32_e32 v112, 0xcf800000, v113
	v_cvt_u32_f32_e32 v112, v112
	v_cvt_u32_f32_e32 v113, v113
	v_lshl_add_u64 v[116:117], v[146:147], 3, s[6:7]
	global_atomic_add_x2 v[116:117], v[112:113], off
.LBB0_1308:
	s_or_b64 exec, exec, s[48:49]
	v_or_b32_e32 v112, 16, v146
	s_waitcnt lgkmcnt(0)
	v_ashrrev_i32_e32 v113, 31, v112
	v_lshlrev_b64 v[116:117], 11, v[112:113]
	v_lshl_add_u64 v[126:127], v[116:117], 0, v[144:145]
	v_lshl_add_u64 v[156:157], v[126:127], 2, s[28:29]
	global_load_dwordx4 v[116:119], v[156:157], off nt
	global_load_dwordx4 v[122:125], v[156:157], off offset:16 nt
	global_load_dwordx4 v[176:179], v[156:157], off offset:512 nt
	global_load_dwordx4 v[180:183], v[156:157], off offset:528 nt
	v_lshl_add_u64 v[126:127], v[126:127], 1, s[46:47]
	s_waitcnt vmcnt(3)
	v_pk_add_f32 v[110:111], v[110:111], v[118:119]
	v_pk_add_f32 v[108:109], v[108:109], v[116:117]
	s_waitcnt vmcnt(2)
	v_pk_add_f32 v[106:107], v[106:107], v[124:125]
	v_pk_add_f32 v[104:105], v[104:105], v[122:123]
	v_cvt_pk_bf16_f32 v116, v108, v109
	v_cvt_pk_bf16_f32 v117, v110, v111
	v_cvt_pk_bf16_f32 v118, v104, v105
	v_cvt_pk_bf16_f32 v119, v106, v107
	global_store_dwordx4 v[156:157], v[108:111], off nt
	global_store_dwordx4 v[156:157], v[104:107], off offset:16 nt
	global_store_dwordx4 v[126:127], v[116:119], off
	s_nop 1
	v_mul_f32_e32 v109, v109, v109
	v_mul_f32_e32 v111, v111, v111
	v_mul_f32_e32 v105, v105, v105
	v_mul_f32_e32 v107, v107, v107
	v_fmac_f32_e32 v109, v108, v108
	v_fmac_f32_e32 v111, v110, v110
	v_fmac_f32_e32 v105, v104, v104
	v_fmac_f32_e32 v107, v106, v106
	v_add_f32_e32 v104, v109, v111
	v_add_f32_e32 v105, v105, v107
	v_add_f32_e32 v108, v104, v105
	s_waitcnt vmcnt(4)
	v_pk_add_f32 v[102:103], v[102:103], v[178:179]
	v_pk_add_f32 v[100:101], v[100:101], v[176:177]
	s_waitcnt vmcnt(3)
	v_pk_add_f32 v[106:107], v[98:99], v[182:183]
	v_pk_add_f32 v[104:105], v[96:97], v[180:181]
	v_mul_f32_e32 v96, v101, v101
	v_mul_f32_e32 v97, v103, v103
	v_mul_f32_e32 v98, v105, v105
	v_mul_f32_e32 v99, v107, v107
	v_fmac_f32_e32 v96, v100, v100
	v_fmac_f32_e32 v97, v102, v102
	v_fmac_f32_e32 v98, v104, v104
	v_fmac_f32_e32 v99, v106, v106
	v_add_f32_e32 v96, v96, v97
	v_add_f32_e32 v97, v98, v99
	v_add_f32_e32 v96, v96, v97
	v_add_f32_e32 v96, v108, v96
	ds_bpermute_b32 v97, v120, v96
	global_store_dwordx4 v[156:157], v[100:103], off offset:512 nt
	global_store_dwordx4 v[156:157], v[104:107], off offset:528 nt
	v_cvt_pk_bf16_f32 v98, v100, v101
	v_cvt_pk_bf16_f32 v99, v102, v103
	v_cvt_pk_bf16_f32 v100, v104, v105
	s_waitcnt lgkmcnt(0)
	v_add_f32_e32 v96, v96, v97
	ds_bpermute_b32 v97, v114, v96
	v_cvt_pk_bf16_f32 v101, v106, v107
	global_store_dwordx4 v[126:127], v[98:101], off offset:256
	s_and_saveexec_b64 s[48:49], s[2:3]
	s_cbranch_execz .LBB0_1310
	s_waitcnt lgkmcnt(0)
	v_add_f32_e32 v96, v96, v97
	v_mul_f32_e32 v96, 0x4b800000, v96
	v_trunc_f32_e32 v96, v96
	v_mul_f32_e32 v97, 0x2f800000, v96
	v_floor_f32_e32 v97, v97
	v_fmac_f32_e32 v96, 0xcf800000, v97
	v_cvt_u32_f32_e32 v96, v96
	v_cvt_u32_f32_e32 v97, v97
	v_lshl_add_u64 v[98:99], v[112:113], 3, s[6:7]
	global_atomic_add_x2 v[98:99], v[96:97], off
; __device__ __forceinline__ u32x4 pack8(const f32x4 a, const f32x4 b) { u32x4 w; w.x = cvt_pk_bf16(a[0], a[1]); w.y = cvt_pk_bf16(a[2], a[3]); w.z = cvt_pk_bf16(b[0], b[1]); w.w = cvt_pk_bf16(b[2], b[3]); return w; }
; __device__ __forceinline__ void ss_add(ssq_t* p, float sq) { __hip_atomic_fetch_add(p, (ssq_t)(sq * 16777216.0f), __ATOMIC_RELAXED, __HIP_MEMORY_SCOPE_AGENT); }
; __device__ __forceinline__ float dot4(const f32x4 a) { return (a[0] * a[0] + a[1] * a[1]) + (a[2] * a[2] + a[3] * a[3]); }
;     __device__ __forceinline__ void operator()(const f32x4 (&acc)[2][2][4][2], const Unit& u, int wr, int wc, int fr, int fq) const {
;     ...
;             for (int m = 0; m < 4; ++m) { const int row = row0 + ai * HALF + m * 16; const size_t off = (size_t)row * 2048 + col0; float sq = 0.f;
; #pragma unroll
;                 for (int bj = 0; bj < 2; ++bj) {
;                     const f32x4 x0 = __builtin_nontemporal_load((const f32x4*)(xin + off + bj * HALF)), x1 = __builtin_nontemporal_load((const f32x4*)(xin + off + bj * HALF + 4));
;                     const f32x4 v0 = x0 + acc[ai][bj][m][0] * alpha, v1 = x1 + acc[ai][bj][m][1] * alpha;
;                     __builtin_nontemporal_store(v0, (f32x4*)(xout + off + bj * HALF)); __builtin_nontemporal_store(v1, (f32x4*)(xout + off + bj * HALF + 4));
;                     if (WRITE_XB) *(u32x4*)(xb + off + bj * HALF) = pack8(v0, v1); sq += dot4(v0) + dot4(v1); }
;                 sq += __shfl_xor(sq, 16); sq += __shfl_xor(sq, 32);
;                 if (fq == 0) ss_add(ssout + row, sq); }
.LBB0_1310:
	s_or_b64 exec, exec, s[48:49]
	v_or_b32_e32 v96, 32, v146
	s_waitcnt lgkmcnt(0)
	v_ashrrev_i32_e32 v97, 31, v96
	v_lshlrev_b64 v[98:99], 11, v[96:97]
	v_lshl_add_u64 v[106:107], v[98:99], 0, v[144:145]
	v_lshl_add_u64 v[108:109], v[106:107], 2, s[28:29]
	global_load_dwordx4 v[98:101], v[108:109], off nt
	global_load_dwordx4 v[102:105], v[108:109], off offset:16 nt
	global_load_dwordx4 v[176:179], v[108:109], off offset:512 nt
	global_load_dwordx4 v[180:183], v[108:109], off offset:528 nt
	v_lshl_add_u64 v[106:107], v[106:107], 1, s[46:47]
	s_waitcnt vmcnt(3)
	v_pk_add_f32 v[94:95], v[94:95], v[100:101]
	v_pk_add_f32 v[92:93], v[92:93], v[98:99]
	s_waitcnt vmcnt(2)
	v_pk_add_f32 v[90:91], v[90:91], v[104:105]
	v_pk_add_f32 v[88:89], v[88:89], v[102:103]
	v_cvt_pk_bf16_f32 v98, v92, v93
	v_cvt_pk_bf16_f32 v99, v94, v95
	v_cvt_pk_bf16_f32 v100, v88, v89
	v_cvt_pk_bf16_f32 v101, v90, v91
	global_store_dwordx4 v[108:109], v[92:95], off nt
	global_store_dwordx4 v[108:109], v[88:91], off offset:16 nt
	global_store_dwordx4 v[106:107], v[98:101], off
	s_nop 1
	v_mul_f32_e32 v93, v93, v93
	v_mul_f32_e32 v95, v95, v95
	v_mul_f32_e32 v89, v89, v89
	v_mul_f32_e32 v91, v91, v91
	v_fmac_f32_e32 v93, v92, v92
	v_fmac_f32_e32 v95, v94, v94
	v_fmac_f32_e32 v89, v88, v88
	v_fmac_f32_e32 v91, v90, v90
	v_add_f32_e32 v88, v93, v95
	v_add_f32_e32 v89, v89, v91
	v_add_f32_e32 v92, v88, v89
	s_waitcnt vmcnt(4)
	v_pk_add_f32 v[86:87], v[86:87], v[178:179]
	v_pk_add_f32 v[84:85], v[84:85], v[176:177]
	s_waitcnt vmcnt(3)
	v_pk_add_f32 v[90:91], v[82:83], v[182:183]
	v_pk_add_f32 v[88:89], v[80:81], v[180:181]
	v_mul_f32_e32 v80, v85, v85
	v_mul_f32_e32 v81, v87, v87
	v_mul_f32_e32 v82, v89, v89
	v_mul_f32_e32 v83, v91, v91
	v_fmac_f32_e32 v80, v84, v84
	v_fmac_f32_e32 v81, v86, v86
	v_fmac_f32_e32 v82, v88, v88
	v_fmac_f32_e32 v83, v90, v90
	v_add_f32_e32 v80, v80, v81
	v_add_f32_e32 v81, v82, v83
	v_add_f32_e32 v80, v80, v81
	v_add_f32_e32 v80, v92, v80
	ds_bpermute_b32 v81, v120, v80
	global_store_dwordx4 v[108:109], v[84:87], off offset:512 nt
	global_store_dwordx4 v[108:109], v[88:91], off offset:528 nt
	v_cvt_pk_bf16_f32 v82, v84, v85
	v_cvt_pk_bf16_f32 v83, v86, v87
	v_cvt_pk_bf16_f32 v84, v88, v89
	s_waitcnt lgkmcnt(0)
	v_add_f32_e32 v80, v80, v81
	ds_bpermute_b32 v81, v114, v80
	v_cvt_pk_bf16_f32 v85, v90, v91
	global_store_dwordx4 v[106:107], v[82:85], off offset:256
	s_and_saveexec_b64 s[48:49], s[2:3]
	s_cbranch_execz .LBB0_1312
	s_waitcnt lgkmcnt(0)
	v_add_f32_e32 v80, v80, v81
	v_mul_f32_e32 v80, 0x4b800000, v80
	v_trunc_f32_e32 v80, v80
	v_mul_f32_e32 v81, 0x2f800000, v80
	v_floor_f32_e32 v81, v81
	v_fmac_f32_e32 v80, 0xcf800000, v81
	v_cvt_u32_f32_e32 v80, v80
	v_cvt_u32_f32_e32 v81, v81
	v_lshl_add_u64 v[82:83], v[96:97], 3, s[6:7]
	global_atomic_add_x2 v[82:83], v[80:81], off
.LBB0_1312:
	s_or_b64 exec, exec, s[48:49]
	v_or_b32_e32 v80, 48, v146
	s_waitcnt lgkmcnt(0)
	v_ashrrev_i32_e32 v81, 31, v80
	v_lshlrev_b64 v[82:83], 11, v[80:81]
	v_lshl_add_u64 v[90:91], v[82:83], 0, v[144:145]
	v_lshl_add_u64 v[92:93], v[90:91], 2, s[28:29]
	global_load_dwordx4 v[82:85], v[92:93], off nt
	global_load_dwordx4 v[86:89], v[92:93], off offset:16 nt
	global_load_dwordx4 v[176:179], v[92:93], off offset:512 nt
	global_load_dwordx4 v[180:183], v[92:93], off offset:528 nt
	v_lshl_add_u64 v[90:91], v[90:91], 1, s[46:47]
	s_waitcnt vmcnt(3)
	v_pk_add_f32 v[78:79], v[78:79], v[84:85]
	v_pk_add_f32 v[76:77], v[76:77], v[82:83]
	s_waitcnt vmcnt(2)
	v_pk_add_f32 v[74:75], v[74:75], v[88:89]
	v_pk_add_f32 v[72:73], v[72:73], v[86:87]
	v_cvt_pk_bf16_f32 v82, v76, v77
	v_cvt_pk_bf16_f32 v83, v78, v79
	v_cvt_pk_bf16_f32 v84, v72, v73
	v_cvt_pk_bf16_f32 v85, v74, v75
	global_store_dwordx4 v[92:93], v[76:79], off nt
	global_store_dwordx4 v[92:93], v[72:75], off offset:16 nt
	global_store_dwordx4 v[90:91], v[82:85], off
	s_nop 1
	v_mul_f32_e32 v77, v77, v77
	v_mul_f32_e32 v79, v79, v79
	v_mul_f32_e32 v73, v73, v73
	v_mul_f32_e32 v75, v75, v75
	v_fmac_f32_e32 v77, v76, v76
	v_fmac_f32_e32 v79, v78, v78
	v_fmac_f32_e32 v73, v72, v72
	v_fmac_f32_e32 v75, v74, v74
	v_add_f32_e32 v72, v77, v79
	v_add_f32_e32 v73, v73, v75
	v_add_f32_e32 v76, v72, v73
	s_waitcnt vmcnt(4)
	v_pk_add_f32 v[70:71], v[70:71], v[178:179]
	v_pk_add_f32 v[68:69], v[68:69], v[176:177]
	s_waitcnt vmcnt(3)
	v_pk_add_f32 v[74:75], v[66:67], v[182:183]
	v_pk_add_f32 v[72:73], v[64:65], v[180:181]
	v_mul_f32_e32 v64, v69, v69
	v_mul_f32_e32 v65, v71, v71
	v_mul_f32_e32 v66, v73, v73
	v_mul_f32_e32 v67, v75, v75
	v_fmac_f32_e32 v64, v68, v68
	v_fmac_f32_e32 v65, v70, v70
	v_fmac_f32_e32 v66, v72, v72
	v_fmac_f32_e32 v67, v74, v74
	v_add_f32_e32 v64, v64, v65
	v_add_f32_e32 v65, v66, v67
	v_add_f32_e32 v64, v64, v65
	v_add_f32_e32 v64, v76, v64
	ds_bpermute_b32 v65, v120, v64
	global_store_dwordx4 v[92:93], v[68:71], off offset:512 nt
	global_store_dwordx4 v[92:93], v[72:75], off offset:528 nt
	v_cvt_pk_bf16_f32 v66, v68, v69
	v_cvt_pk_bf16_f32 v67, v70, v71
	v_cvt_pk_bf16_f32 v68, v72, v73
	s_waitcnt lgkmcnt(0)
	v_add_f32_e32 v64, v64, v65
	ds_bpermute_b32 v65, v114, v64
	v_cvt_pk_bf16_f32 v69, v74, v75
	global_store_dwordx4 v[90:91], v[66:69], off offset:256
	s_and_saveexec_b64 s[48:49], s[2:3]
	s_cbranch_execz .LBB0_1314
	s_waitcnt lgkmcnt(0)
	v_add_f32_e32 v64, v64, v65
	v_mul_f32_e32 v64, 0x4b800000, v64
	v_trunc_f32_e32 v64, v64
	v_mul_f32_e32 v65, 0x2f800000, v64
	v_floor_f32_e32 v65, v65
	v_fmac_f32_e32 v64, 0xcf800000, v65
	v_cvt_u32_f32_e32 v64, v64
	v_cvt_u32_f32_e32 v65, v65
	v_lshl_add_u64 v[66:67], v[80:81], 3, s[6:7]
	global_atomic_add_x2 v[66:67], v[64:65], off
; __device__ __forceinline__ u32x4 pack8(const f32x4 a, const f32x4 b) { u32x4 w; w.x = cvt_pk_bf16(a[0], a[1]); w.y = cvt_pk_bf16(a[2], a[3]); w.z = cvt_pk_bf16(b[0], b[1]); w.w = cvt_pk_bf16(b[2], b[3]); return w; }
; __device__ __forceinline__ void ss_add(ssq_t* p, float sq) { __hip_atomic_fetch_add(p, (ssq_t)(sq * 16777216.0f), __ATOMIC_RELAXED, __HIP_MEMORY_SCOPE_AGENT); }
; __device__ __forceinline__ float dot4(const f32x4 a) { return (a[0] * a[0] + a[1] * a[1]) + (a[2] * a[2] + a[3] * a[3]); }
;     __device__ __forceinline__ void operator()(const f32x4 (&acc)[2][2][4][2], const Unit& u, int wr, int wc, int fr, int fq) const {
;     ...
;             for (int m = 0; m < 4; ++m) { const int row = row0 + ai * HALF + m * 16; const size_t off = (size_t)row * 2048 + col0; float sq = 0.f;
; #pragma unroll
;                 for (int bj = 0; bj < 2; ++bj) {
;                     const f32x4 x0 = __builtin_nontemporal_load((const f32x4*)(xin + off + bj * HALF)), x1 = __builtin_nontemporal_load((const f32x4*)(xin + off + bj * HALF + 4));
;                     const f32x4 v0 = x0 + acc[ai][bj][m][0] * alpha, v1 = x1 + acc[ai][bj][m][1] * alpha;
;                     __builtin_nontemporal_store(v0, (f32x4*)(xout + off + bj * HALF)); __builtin_nontemporal_store(v1, (f32x4*)(xout + off + bj * HALF + 4));
;                     if (WRITE_XB) *(u32x4*)(xb + off + bj * HALF) = pack8(v0, v1); sq += dot4(v0) + dot4(v1); }
;                 sq += __shfl_xor(sq, 16); sq += __shfl_xor(sq, 32);
;                 if (fq == 0) ss_add(ssout + row, sq); }
.LBB0_1314:
	s_or_b64 exec, exec, s[48:49]
	v_add_u32_e32 v64, 0x80, v146
	s_waitcnt lgkmcnt(0)
	v_ashrrev_i32_e32 v65, 31, v64
	v_lshlrev_b64 v[66:67], 11, v[64:65]
	v_lshl_add_u64 v[74:75], v[66:67], 0, v[144:145]
	v_lshl_add_u64 v[76:77], v[74:75], 2, s[28:29]
	global_load_dwordx4 v[66:69], v[76:77], off nt
	global_load_dwordx4 v[70:73], v[76:77], off offset:16 nt
	global_load_dwordx4 v[176:179], v[76:77], off offset:512 nt
	global_load_dwordx4 v[180:183], v[76:77], off offset:528 nt
	v_lshl_add_u64 v[74:75], v[74:75], 1, s[46:47]
	s_waitcnt vmcnt(3)
	v_pk_add_f32 v[62:63], v[62:63], v[68:69]
	v_pk_add_f32 v[60:61], v[60:61], v[66:67]
	s_waitcnt vmcnt(2)
	v_pk_add_f32 v[58:59], v[58:59], v[72:73]
	v_pk_add_f32 v[56:57], v[56:57], v[70:71]
	v_cvt_pk_bf16_f32 v66, v60, v61
	v_cvt_pk_bf16_f32 v67, v62, v63
	v_cvt_pk_bf16_f32 v68, v56, v57
	v_cvt_pk_bf16_f32 v69, v58, v59
	global_store_dwordx4 v[76:77], v[60:63], off nt
	global_store_dwordx4 v[76:77], v[56:59], off offset:16 nt
	global_store_dwordx4 v[74:75], v[66:69], off
	s_nop 1
	v_mul_f32_e32 v61, v61, v61
	v_mul_f32_e32 v63, v63, v63
	v_mul_f32_e32 v57, v57, v57
	v_mul_f32_e32 v59, v59, v59
	v_fmac_f32_e32 v61, v60, v60
	v_fmac_f32_e32 v63, v62, v62
	v_fmac_f32_e32 v57, v56, v56
	v_fmac_f32_e32 v59, v58, v58
	v_add_f32_e32 v56, v61, v63
	v_add_f32_e32 v57, v57, v59
	v_add_f32_e32 v60, v56, v57
	s_waitcnt vmcnt(4)
	v_pk_add_f32 v[54:55], v[54:55], v[178:179]
	v_pk_add_f32 v[52:53], v[52:53], v[176:177]
	s_waitcnt vmcnt(3)
	v_pk_add_f32 v[58:59], v[50:51], v[182:183]
	v_pk_add_f32 v[56:57], v[48:49], v[180:181]
	v_mul_f32_e32 v48, v53, v53
	v_mul_f32_e32 v49, v55, v55
	v_mul_f32_e32 v50, v57, v57
	v_mul_f32_e32 v51, v59, v59
	v_fmac_f32_e32 v48, v52, v52
	v_fmac_f32_e32 v49, v54, v54
	v_fmac_f32_e32 v50, v56, v56
	v_fmac_f32_e32 v51, v58, v58
	v_add_f32_e32 v48, v48, v49
	v_add_f32_e32 v49, v50, v51
	v_add_f32_e32 v48, v48, v49
	v_add_f32_e32 v48, v60, v48
	ds_bpermute_b32 v49, v120, v48
	global_store_dwordx4 v[76:77], v[52:55], off offset:512 nt
	global_store_dwordx4 v[76:77], v[56:59], off offset:528 nt
	v_cvt_pk_bf16_f32 v50, v52, v53
	v_cvt_pk_bf16_f32 v51, v54, v55
	v_cvt_pk_bf16_f32 v52, v56, v57
	s_waitcnt lgkmcnt(0)
	v_add_f32_e32 v48, v48, v49
	ds_bpermute_b32 v49, v114, v48
	v_cvt_pk_bf16_f32 v53, v58, v59
	global_store_dwordx4 v[74:75], v[50:53], off offset:256
	s_and_saveexec_b64 s[48:49], s[2:3]
	s_cbranch_execz .LBB0_1316
	s_waitcnt lgkmcnt(0)
	v_add_f32_e32 v48, v48, v49
	v_mul_f32_e32 v48, 0x4b800000, v48
	v_trunc_f32_e32 v48, v48
	v_mul_f32_e32 v49, 0x2f800000, v48
	v_floor_f32_e32 v49, v49
	v_fmac_f32_e32 v48, 0xcf800000, v49
	v_cvt_u32_f32_e32 v48, v48
	v_cvt_u32_f32_e32 v49, v49
	v_lshl_add_u64 v[50:51], v[64:65], 3, s[6:7]
	global_atomic_add_x2 v[50:51], v[48:49], off
.LBB0_1316:
	s_or_b64 exec, exec, s[48:49]
	v_add_u32_e32 v48, 0x90, v146
	s_waitcnt lgkmcnt(0)
	v_ashrrev_i32_e32 v49, 31, v48
	v_lshlrev_b64 v[50:51], 11, v[48:49]
	v_lshl_add_u64 v[58:59], v[50:51], 0, v[144:145]
	v_lshl_add_u64 v[60:61], v[58:59], 2, s[28:29]
	global_load_dwordx4 v[50:53], v[60:61], off nt
	global_load_dwordx4 v[54:57], v[60:61], off offset:16 nt
	global_load_dwordx4 v[176:179], v[60:61], off offset:512 nt
	global_load_dwordx4 v[180:183], v[60:61], off offset:528 nt
	v_lshl_add_u64 v[58:59], v[58:59], 1, s[46:47]
	s_waitcnt vmcnt(3)
	v_pk_add_f32 v[46:47], v[46:47], v[52:53]
	v_pk_add_f32 v[44:45], v[44:45], v[50:51]
	s_waitcnt vmcnt(2)
	v_pk_add_f32 v[42:43], v[42:43], v[56:57]
	v_pk_add_f32 v[40:41], v[40:41], v[54:55]
	v_cvt_pk_bf16_f32 v50, v44, v45
	v_cvt_pk_bf16_f32 v51, v46, v47
	v_cvt_pk_bf16_f32 v52, v40, v41
	v_cvt_pk_bf16_f32 v53, v42, v43
	global_store_dwordx4 v[60:61], v[44:47], off nt
	global_store_dwordx4 v[60:61], v[40:43], off offset:16 nt
	global_store_dwordx4 v[58:59], v[50:53], off
	s_nop 1
	v_mul_f32_e32 v45, v45, v45
	v_mul_f32_e32 v47, v47, v47
	v_mul_f32_e32 v41, v41, v41
	v_mul_f32_e32 v43, v43, v43
	v_fmac_f32_e32 v45, v44, v44
	v_fmac_f32_e32 v47, v46, v46
	v_fmac_f32_e32 v41, v40, v40
	v_fmac_f32_e32 v43, v42, v42
	v_add_f32_e32 v40, v45, v47
	v_add_f32_e32 v41, v41, v43
	v_add_f32_e32 v44, v40, v41
	s_waitcnt vmcnt(4)
	v_pk_add_f32 v[38:39], v[38:39], v[178:179]
	v_pk_add_f32 v[36:37], v[36:37], v[176:177]
	s_waitcnt vmcnt(3)
	v_pk_add_f32 v[42:43], v[34:35], v[182:183]
	v_pk_add_f32 v[40:41], v[32:33], v[180:181]
	v_mul_f32_e32 v32, v37, v37
	v_mul_f32_e32 v33, v39, v39
	v_mul_f32_e32 v34, v41, v41
	v_mul_f32_e32 v35, v43, v43
	v_fmac_f32_e32 v32, v36, v36
	v_fmac_f32_e32 v33, v38, v38
	v_fmac_f32_e32 v34, v40, v40
	v_fmac_f32_e32 v35, v42, v42
	v_add_f32_e32 v32, v32, v33
	v_add_f32_e32 v33, v34, v35
	v_add_f32_e32 v32, v32, v33
	v_add_f32_e32 v32, v44, v32
	ds_bpermute_b32 v33, v120, v32
	global_store_dwordx4 v[60:61], v[36:39], off offset:512 nt
	global_store_dwordx4 v[60:61], v[40:43], off offset:528 nt
	v_cvt_pk_bf16_f32 v34, v36, v37
	v_cvt_pk_bf16_f32 v35, v38, v39
	v_cvt_pk_bf16_f32 v36, v40, v41
	s_waitcnt lgkmcnt(0)
	v_add_f32_e32 v32, v32, v33
	ds_bpermute_b32 v33, v114, v32
	v_cvt_pk_bf16_f32 v37, v42, v43
	global_store_dwordx4 v[58:59], v[34:37], off offset:256
	s_and_saveexec_b64 s[48:49], s[2:3]
	s_cbranch_execz .LBB0_1318
	s_waitcnt lgkmcnt(0)
	v_add_f32_e32 v32, v32, v33
	v_mul_f32_e32 v32, 0x4b800000, v32
	v_trunc_f32_e32 v32, v32
	v_mul_f32_e32 v33, 0x2f800000, v32
	v_floor_f32_e32 v33, v33
	v_fmac_f32_e32 v32, 0xcf800000, v33
	v_cvt_u32_f32_e32 v32, v32
	v_cvt_u32_f32_e32 v33, v33
	v_lshl_add_u64 v[34:35], v[48:49], 3, s[6:7]
	global_atomic_add_x2 v[34:35], v[32:33], off
; __device__ __forceinline__ u32x4 pack8(const f32x4 a, const f32x4 b) { u32x4 w; w.x = cvt_pk_bf16(a[0], a[1]); w.y = cvt_pk_bf16(a[2], a[3]); w.z = cvt_pk_bf16(b[0], b[1]); w.w = cvt_pk_bf16(b[2], b[3]); return w; }
; __device__ __forceinline__ void ss_add(ssq_t* p, float sq) { __hip_atomic_fetch_add(p, (ssq_t)(sq * 16777216.0f), __ATOMIC_RELAXED, __HIP_MEMORY_SCOPE_AGENT); }
; __device__ __forceinline__ float dot4(const f32x4 a) { return (a[0] * a[0] + a[1] * a[1]) + (a[2] * a[2] + a[3] * a[3]); }
;     __device__ __forceinline__ void operator()(const f32x4 (&acc)[2][2][4][2], const Unit& u, int wr, int wc, int fr, int fq) const {
;     ...
;             for (int m = 0; m < 4; ++m) { const int row = row0 + ai * HALF + m * 16; const size_t off = (size_t)row * 2048 + col0; float sq = 0.f;
; #pragma unroll
;                 for (int bj = 0; bj < 2; ++bj) {
;                     const f32x4 x0 = __builtin_nontemporal_load((const f32x4*)(xin + off + bj * HALF)), x1 = __builtin_nontemporal_load((const f32x4*)(xin + off + bj * HALF + 4));
;                     const f32x4 v0 = x0 + acc[ai][bj][m][0] * alpha, v1 = x1 + acc[ai][bj][m][1] * alpha;
;                     __builtin_nontemporal_store(v0, (f32x4*)(xout + off + bj * HALF)); __builtin_nontemporal_store(v1, (f32x4*)(xout + off + bj * HALF + 4));
;                     if (WRITE_XB) *(u32x4*)(xb + off + bj * HALF) = pack8(v0, v1); sq += dot4(v0) + dot4(v1); }
;                 sq += __shfl_xor(sq, 16); sq += __shfl_xor(sq, 32);
;                 if (fq == 0) ss_add(ssout + row, sq); }
.LBB0_1318:
	s_or_b64 exec, exec, s[48:49]
	v_add_u32_e32 v32, 0xa0, v146
	s_waitcnt lgkmcnt(0)
	v_ashrrev_i32_e32 v33, 31, v32
	v_lshlrev_b64 v[34:35], 11, v[32:33]
	v_lshl_add_u64 v[42:43], v[34:35], 0, v[144:145]
	v_lshl_add_u64 v[44:45], v[42:43], 2, s[28:29]
	global_load_dwordx4 v[34:37], v[44:45], off nt
	global_load_dwordx4 v[38:41], v[44:45], off offset:16 nt
	global_load_dwordx4 v[176:179], v[44:45], off offset:512 nt
	global_load_dwordx4 v[180:183], v[44:45], off offset:528 nt
	v_lshl_add_u64 v[42:43], v[42:43], 1, s[46:47]
	s_waitcnt vmcnt(3)
	v_pk_add_f32 v[30:31], v[30:31], v[36:37]
	v_pk_add_f32 v[28:29], v[28:29], v[34:35]
	s_waitcnt vmcnt(2)
	v_pk_add_f32 v[26:27], v[26:27], v[40:41]
	v_pk_add_f32 v[24:25], v[24:25], v[38:39]
	v_cvt_pk_bf16_f32 v34, v28, v29
	v_cvt_pk_bf16_f32 v35, v30, v31
	v_cvt_pk_bf16_f32 v36, v24, v25
	v_cvt_pk_bf16_f32 v37, v26, v27
	global_store_dwordx4 v[44:45], v[28:31], off nt
	global_store_dwordx4 v[44:45], v[24:27], off offset:16 nt
	global_store_dwordx4 v[42:43], v[34:37], off
	s_nop 1
	v_mul_f32_e32 v29, v29, v29
	v_mul_f32_e32 v31, v31, v31
	v_mul_f32_e32 v25, v25, v25
	v_mul_f32_e32 v27, v27, v27
	v_fmac_f32_e32 v29, v28, v28
	v_fmac_f32_e32 v31, v30, v30
	v_fmac_f32_e32 v25, v24, v24
	v_fmac_f32_e32 v27, v26, v26
	v_add_f32_e32 v24, v29, v31
	v_add_f32_e32 v25, v25, v27
	v_add_f32_e32 v28, v24, v25
	s_waitcnt vmcnt(4)
	v_pk_add_f32 v[22:23], v[22:23], v[178:179]
	v_pk_add_f32 v[20:21], v[20:21], v[176:177]
	s_waitcnt vmcnt(3)
	v_pk_add_f32 v[26:27], v[18:19], v[182:183]
	v_pk_add_f32 v[24:25], v[16:17], v[180:181]
	v_mul_f32_e32 v16, v21, v21
	v_mul_f32_e32 v17, v23, v23
	v_mul_f32_e32 v18, v25, v25
	v_mul_f32_e32 v19, v27, v27
	v_fmac_f32_e32 v16, v20, v20
	v_fmac_f32_e32 v17, v22, v22
	v_fmac_f32_e32 v18, v24, v24
	v_fmac_f32_e32 v19, v26, v26
	v_add_f32_e32 v16, v16, v17
	v_add_f32_e32 v17, v18, v19
	v_add_f32_e32 v16, v16, v17
	v_add_f32_e32 v16, v28, v16
	ds_bpermute_b32 v17, v120, v16
	global_store_dwordx4 v[44:45], v[20:23], off offset:512 nt
	global_store_dwordx4 v[44:45], v[24:27], off offset:528 nt
	v_cvt_pk_bf16_f32 v18, v20, v21
	v_cvt_pk_bf16_f32 v19, v22, v23
	v_cvt_pk_bf16_f32 v20, v24, v25
	s_waitcnt lgkmcnt(0)
	v_add_f32_e32 v16, v16, v17
	ds_bpermute_b32 v17, v114, v16
	v_cvt_pk_bf16_f32 v21, v26, v27
	global_store_dwordx4 v[42:43], v[18:21], off offset:256
	s_and_saveexec_b64 s[48:49], s[2:3]
	s_cbranch_execz .LBB0_1320
	s_waitcnt lgkmcnt(0)
	v_add_f32_e32 v16, v16, v17
	v_mul_f32_e32 v16, 0x4b800000, v16
	v_trunc_f32_e32 v16, v16
	v_mul_f32_e32 v17, 0x2f800000, v16
	v_floor_f32_e32 v17, v17
	v_fmac_f32_e32 v16, 0xcf800000, v17
	v_cvt_u32_f32_e32 v16, v16
	v_cvt_u32_f32_e32 v17, v17
	v_lshl_add_u64 v[18:19], v[32:33], 3, s[6:7]
	global_atomic_add_x2 v[18:19], v[16:17], off
.LBB0_1320:
	s_or_b64 exec, exec, s[48:49]
	v_add_u32_e32 v16, 0xb0, v146
	s_waitcnt lgkmcnt(0)
	v_ashrrev_i32_e32 v17, 31, v16
	v_lshlrev_b64 v[18:19], 11, v[16:17]
	v_lshl_add_u64 v[26:27], v[18:19], 0, v[144:145]
	v_lshl_add_u64 v[28:29], v[26:27], 2, s[28:29]
	global_load_dwordx4 v[18:21], v[28:29], off nt
	global_load_dwordx4 v[22:25], v[28:29], off offset:16 nt
	global_load_dwordx4 v[176:179], v[28:29], off offset:512 nt
	global_load_dwordx4 v[180:183], v[28:29], off offset:528 nt
	v_lshl_add_u64 v[26:27], v[26:27], 1, s[46:47]
	s_waitcnt vmcnt(3)
	v_pk_add_f32 v[14:15], v[14:15], v[20:21]
	v_pk_add_f32 v[12:13], v[12:13], v[18:19]
	s_waitcnt vmcnt(2)
	v_pk_add_f32 v[10:11], v[10:11], v[24:25]
	v_pk_add_f32 v[8:9], v[8:9], v[22:23]
	v_cvt_pk_bf16_f32 v18, v12, v13
	v_cvt_pk_bf16_f32 v19, v14, v15
	v_cvt_pk_bf16_f32 v20, v8, v9
	v_cvt_pk_bf16_f32 v21, v10, v11
	global_store_dwordx4 v[28:29], v[12:15], off nt
	global_store_dwordx4 v[28:29], v[8:11], off offset:16 nt
	global_store_dwordx4 v[26:27], v[18:21], off
	s_nop 1
	v_mul_f32_e32 v13, v13, v13
	v_mul_f32_e32 v15, v15, v15
	v_mul_f32_e32 v9, v9, v9
	v_mul_f32_e32 v11, v11, v11
	v_fmac_f32_e32 v13, v12, v12
	v_fmac_f32_e32 v15, v14, v14
	v_fmac_f32_e32 v9, v8, v8
	v_fmac_f32_e32 v11, v10, v10
	v_add_f32_e32 v8, v13, v15
	v_add_f32_e32 v9, v9, v11
	v_add_f32_e32 v12, v8, v9
	s_waitcnt vmcnt(4)
	v_pk_add_f32 v[6:7], v[6:7], v[178:179]
	v_pk_add_f32 v[4:5], v[4:5], v[176:177]
	s_waitcnt vmcnt(3)
	v_pk_add_f32 v[10:11], v[2:3], v[182:183]
	v_pk_add_f32 v[8:9], v[0:1], v[180:181]
	v_mul_f32_e32 v0, v5, v5
	v_mul_f32_e32 v1, v7, v7
	v_mul_f32_e32 v2, v9, v9
	v_mul_f32_e32 v3, v11, v11
	v_fmac_f32_e32 v0, v4, v4
	v_fmac_f32_e32 v1, v6, v6
	v_fmac_f32_e32 v2, v8, v8
	v_fmac_f32_e32 v3, v10, v10
	v_add_f32_e32 v0, v0, v1
	v_add_f32_e32 v1, v2, v3
	v_add_f32_e32 v0, v0, v1
	v_add_f32_e32 v0, v12, v0
	ds_bpermute_b32 v1, v120, v0
	global_store_dwordx4 v[28:29], v[4:7], off offset:512 nt
	global_store_dwordx4 v[28:29], v[8:11], off offset:528 nt
	v_cvt_pk_bf16_f32 v2, v4, v5
	v_cvt_pk_bf16_f32 v3, v6, v7
	v_cvt_pk_bf16_f32 v4, v8, v9
	s_waitcnt lgkmcnt(0)
	v_add_f32_e32 v0, v0, v1
	ds_bpermute_b32 v1, v114, v0
	v_cvt_pk_bf16_f32 v5, v10, v11
	global_store_dwordx4 v[26:27], v[2:5], off offset:256
	s_and_saveexec_b64 s[48:49], s[2:3]
	s_cbranch_execz .LBB0_1322
	s_waitcnt lgkmcnt(0)
	v_add_f32_e32 v0, v0, v1
	v_mul_f32_e32 v0, 0x4b800000, v0
	v_trunc_f32_e32 v0, v0
	v_mul_f32_e32 v1, 0x2f800000, v0
	v_floor_f32_e32 v1, v1
	v_fmac_f32_e32 v0, 0xcf800000, v1
	v_cvt_u32_f32_e32 v0, v0
	v_cvt_u32_f32_e32 v1, v1
	v_lshl_add_u64 v[2:3], v[16:17], 3, s[6:7]
	global_atomic_add_x2 v[2:3], v[0:1], off

; __device__ __forceinline__ u32x4 pack8(const f32x4 a, const f32x4 b) { u32x4 w; w.x = cvt_pk_bf16(a[0], a[1]); w.y = cvt_pk_bf16(a[2], a[3]); w.z = cvt_pk_bf16(b[0], b[1]); w.w = cvt_pk_bf16(b[2], b[3]); return w; }
; __device__ __forceinline__ void ss_add(ssq_t* p, float sq) { __hip_atomic_fetch_add(p, (ssq_t)(sq * 16777216.0f), __ATOMIC_RELAXED, __HIP_MEMORY_SCOPE_AGENT); }
; __device__ __forceinline__ float dot4(const f32x4 a) { return (a[0] * a[0] + a[1] * a[1]) + (a[2] * a[2] + a[3] * a[3]); }
;     __device__ __forceinline__ void operator()(const f32x4 (&acc)[2][2][4][2], const Unit& u, int wr, int wc, int fr, int fq) const {
;     ...
;             for (int m = 0; m < 4; ++m) { const int row = row0 + ai * HALF + m * 16; const size_t off = (size_t)row * 2048 + col0; float sq = 0.f;
; #pragma unroll
;                 for (int bj = 0; bj < 2; ++bj) {
;                     const f32x4 x0 = __builtin_nontemporal_load((const f32x4*)(xin + off + bj * HALF)), x1 = __builtin_nontemporal_load((const f32x4*)(xin + off + bj * HALF + 4));
;                     const f32x4 v0 = x0 + acc[ai][bj][m][0] * alpha, v1 = x1 + acc[ai][bj][m][1] * alpha;
;                     __builtin_nontemporal_store(v0, (f32x4*)(xout + off + bj * HALF)); __builtin_nontemporal_store(v1, (f32x4*)(xout + off + bj * HALF + 4));
;                     if (WRITE_XB) *(u32x4*)(xb + off + bj * HALF) = pack8(v0, v1); sq += dot4(v0) + dot4(v1); }
;                 sq += __shfl_xor(sq, 16); sq += __shfl_xor(sq, 32);
;                 if (fq == 0) ss_add(ssout + row, sq); }
.LBB0_1478:
	v_lshl_add_u32 v146, s48, 8, v148
	v_lshl_add_u32 v144, s49, 8, v150
	v_ashrrev_i32_e32 v147, 31, v146
	v_ashrrev_i32_e32 v145, 31, v144
	v_lshlrev_b64 v[156:157], 11, v[146:147]
	v_lshl_add_u64 v[164:165], v[156:157], 0, v[144:145]
	v_lshl_add_u64 v[168:169], v[164:165], 2, s[28:29]
	global_load_dwordx4 v[156:159], v[168:169], off nt
	global_load_dwordx4 v[160:163], v[168:169], off offset:16 nt
	global_load_dwordx4 v[176:179], v[168:169], off offset:512 nt
	global_load_dwordx4 v[180:183], v[168:169], off offset:528 nt
	v_lshl_add_u64 v[170:171], v[164:165], 1, s[46:47]
	s_waitcnt vmcnt(2)
	v_pk_fma_f32 v[126:127], v[126:127], 0.5, v[158:159] op_sel_hi:[1,0,1]
	v_pk_fma_f32 v[124:125], v[124:125], 0.5, v[156:157] op_sel_hi:[1,0,1]
	v_pk_fma_f32 v[158:159], v[122:123], 0.5, v[162:163] op_sel_hi:[1,0,1]
	v_pk_fma_f32 v[156:157], v[120:121], 0.5, v[160:161] op_sel_hi:[1,0,1]
	v_cvt_pk_bf16_f32 v120, v124, v125
	v_cvt_pk_bf16_f32 v121, v126, v127
	v_cvt_pk_bf16_f32 v122, v156, v157
	v_cvt_pk_bf16_f32 v123, v158, v159
	global_store_dwordx4 v[168:169], v[124:127], off nt
	global_store_dwordx4 v[168:169], v[156:159], off offset:16 nt
	global_store_dwordx4 v[170:171], v[120:123], off
	s_nop 1
	v_and_b32_e32 v121, 64, v154
	v_xor_b32_e32 v120, 16, v154
	v_add_u32_e32 v121, 64, v121
	v_xor_b32_e32 v122, 32, v154
	v_cmp_lt_i32_e32 vcc, v120, v121
	v_mul_f32_e32 v123, v127, v127
	v_mul_f32_e32 v127, v159, v159
	v_cndmask_b32_e32 v120, v154, v120, vcc
	v_cmp_lt_i32_e32 vcc, v122, v121
	v_fmac_f32_e32 v123, v126, v126
	v_fmac_f32_e32 v127, v158, v158
	v_cndmask_b32_e32 v121, v154, v122, vcc
	v_mul_f32_e32 v122, v125, v125
	v_mul_f32_e32 v125, v157, v157
	v_fmac_f32_e32 v122, v124, v124
	v_fmac_f32_e32 v125, v156, v156
	v_add_f32_e32 v122, v122, v123
	v_add_f32_e32 v123, v125, v127
	v_add_f32_e32 v126, v122, v123
	v_lshlrev_b32_e32 v120, 2, v120
	s_waitcnt vmcnt(4)
	v_pk_fma_f32 v[118:119], v[118:119], 0.5, v[178:179] op_sel_hi:[1,0,1]
	v_pk_fma_f32 v[116:117], v[116:117], 0.5, v[176:177] op_sel_hi:[1,0,1]
	s_waitcnt vmcnt(3)
	v_pk_fma_f32 v[124:125], v[114:115], 0.5, v[182:183] op_sel_hi:[1,0,1]
	v_pk_fma_f32 v[122:123], v[112:113], 0.5, v[180:181] op_sel_hi:[1,0,1]
	v_mul_f32_e32 v112, v117, v117
	v_mul_f32_e32 v113, v119, v119
	v_mul_f32_e32 v114, v123, v123
	v_mul_f32_e32 v115, v125, v125
	v_fmac_f32_e32 v112, v116, v116
	v_fmac_f32_e32 v113, v118, v118
	v_fmac_f32_e32 v114, v122, v122
	v_fmac_f32_e32 v115, v124, v124
	v_add_f32_e32 v112, v112, v113
	v_add_f32_e32 v113, v114, v115
	v_add_f32_e32 v112, v112, v113
	v_add_f32_e32 v112, v126, v112
	ds_bpermute_b32 v113, v120, v112
	v_lshlrev_b32_e32 v114, 2, v121
	global_store_dwordx4 v[168:169], v[116:119], off offset:512 nt
	global_store_dwordx4 v[168:169], v[122:125], off offset:528 nt
	s_waitcnt lgkmcnt(0)
	v_add_f32_e32 v112, v112, v113
	ds_bpermute_b32 v113, v114, v112
	v_cvt_pk_bf16_f32 v116, v116, v117
	v_cvt_pk_bf16_f32 v117, v118, v119
	v_cvt_pk_bf16_f32 v118, v122, v123
	v_cvt_pk_bf16_f32 v119, v124, v125
	global_store_dwordx4 v[170:171], v[116:119], off offset:256
	s_and_saveexec_b64 s[48:49], s[2:3]
	s_cbranch_execz .LBB0_1480
	s_waitcnt lgkmcnt(0)
	v_add_f32_e32 v112, v112, v113
	v_mul_f32_e32 v112, 0x4b800000, v112
	v_trunc_f32_e32 v112, v112
	v_mul_f32_e32 v113, 0x2f800000, v112
	v_floor_f32_e32 v113, v113
	v_fmac_f32_e32 v112, 0xcf800000, v113
	v_cvt_u32_f32_e32 v112, v112
	v_cvt_u32_f32_e32 v113, v113
	v_lshl_add_u64 v[116:117], v[146:147], 3, s[18:19]
	global_atomic_add_x2 v[116:117], v[112:113], off
.LBB0_1480:
	s_or_b64 exec, exec, s[48:49]
	v_or_b32_e32 v112, 16, v146
	s_waitcnt lgkmcnt(0)
	v_ashrrev_i32_e32 v113, 31, v112
	v_lshlrev_b64 v[116:117], 11, v[112:113]
	v_lshl_add_u64 v[126:127], v[116:117], 0, v[144:145]
	v_lshl_add_u64 v[156:157], v[126:127], 2, s[28:29]
	global_load_dwordx4 v[116:119], v[156:157], off nt
	global_load_dwordx4 v[122:125], v[156:157], off offset:16 nt
	global_load_dwordx4 v[176:179], v[156:157], off offset:512 nt
	global_load_dwordx4 v[180:183], v[156:157], off offset:528 nt
	v_lshl_add_u64 v[126:127], v[126:127], 1, s[46:47]
	s_waitcnt vmcnt(3)
	v_pk_fma_f32 v[110:111], v[110:111], 0.5, v[118:119] op_sel_hi:[1,0,1]
	v_pk_fma_f32 v[108:109], v[108:109], 0.5, v[116:117] op_sel_hi:[1,0,1]
	s_waitcnt vmcnt(2)
	v_pk_fma_f32 v[106:107], v[106:107], 0.5, v[124:125] op_sel_hi:[1,0,1]
	v_pk_fma_f32 v[104:105], v[104:105], 0.5, v[122:123] op_sel_hi:[1,0,1]
	v_cvt_pk_bf16_f32 v116, v108, v109
	v_cvt_pk_bf16_f32 v117, v110, v111
	v_cvt_pk_bf16_f32 v118, v104, v105
	v_cvt_pk_bf16_f32 v119, v106, v107
	global_store_dwordx4 v[156:157], v[108:111], off nt
	global_store_dwordx4 v[156:157], v[104:107], off offset:16 nt
	global_store_dwordx4 v[126:127], v[116:119], off
	s_nop 1
	v_mul_f32_e32 v109, v109, v109
	v_mul_f32_e32 v111, v111, v111
	v_mul_f32_e32 v105, v105, v105
	v_mul_f32_e32 v107, v107, v107
	v_fmac_f32_e32 v109, v108, v108
	v_fmac_f32_e32 v111, v110, v110
	v_fmac_f32_e32 v105, v104, v104
	v_fmac_f32_e32 v107, v106, v106
	v_add_f32_e32 v104, v109, v111
	v_add_f32_e32 v105, v105, v107
	v_add_f32_e32 v108, v104, v105
	s_waitcnt vmcnt(4)
	v_pk_fma_f32 v[102:103], v[102:103], 0.5, v[178:179] op_sel_hi:[1,0,1]
	v_pk_fma_f32 v[100:101], v[100:101], 0.5, v[176:177] op_sel_hi:[1,0,1]
	s_waitcnt vmcnt(3)
	v_pk_fma_f32 v[106:107], v[98:99], 0.5, v[182:183] op_sel_hi:[1,0,1]
	v_pk_fma_f32 v[104:105], v[96:97], 0.5, v[180:181] op_sel_hi:[1,0,1]
	v_mul_f32_e32 v96, v101, v101
	v_mul_f32_e32 v97, v103, v103
	v_mul_f32_e32 v98, v105, v105
	v_mul_f32_e32 v99, v107, v107
	v_fmac_f32_e32 v96, v100, v100
	v_fmac_f32_e32 v97, v102, v102
	v_fmac_f32_e32 v98, v104, v104
	v_fmac_f32_e32 v99, v106, v106
	v_add_f32_e32 v96, v96, v97
	v_add_f32_e32 v97, v98, v99
	v_add_f32_e32 v96, v96, v97
	v_add_f32_e32 v96, v108, v96
	ds_bpermute_b32 v97, v120, v96
	global_store_dwordx4 v[156:157], v[100:103], off offset:512 nt
	global_store_dwordx4 v[156:157], v[104:107], off offset:528 nt
	v_cvt_pk_bf16_f32 v98, v100, v101
	v_cvt_pk_bf16_f32 v99, v102, v103
	v_cvt_pk_bf16_f32 v100, v104, v105
	s_waitcnt lgkmcnt(0)
	v_add_f32_e32 v96, v96, v97
	ds_bpermute_b32 v97, v114, v96
	v_cvt_pk_bf16_f32 v101, v106, v107
	global_store_dwordx4 v[126:127], v[98:101], off offset:256
	s_and_saveexec_b64 s[48:49], s[2:3]
	s_cbranch_execz .LBB0_1482
	s_waitcnt lgkmcnt(0)
	v_add_f32_e32 v96, v96, v97
	v_mul_f32_e32 v96, 0x4b800000, v96
	v_trunc_f32_e32 v96, v96
	v_mul_f32_e32 v97, 0x2f800000, v96
	v_floor_f32_e32 v97, v97
	v_fmac_f32_e32 v96, 0xcf800000, v97
	v_cvt_u32_f32_e32 v96, v96
	v_cvt_u32_f32_e32 v97, v97
	v_lshl_add_u64 v[98:99], v[112:113], 3, s[18:19]
	global_atomic_add_x2 v[98:99], v[96:97], off
; __device__ __forceinline__ u32x4 pack8(const f32x4 a, const f32x4 b) { u32x4 w; w.x = cvt_pk_bf16(a[0], a[1]); w.y = cvt_pk_bf16(a[2], a[3]); w.z = cvt_pk_bf16(b[0], b[1]); w.w = cvt_pk_bf16(b[2], b[3]); return w; }
; __device__ __forceinline__ void ss_add(ssq_t* p, float sq) { __hip_atomic_fetch_add(p, (ssq_t)(sq * 16777216.0f), __ATOMIC_RELAXED, __HIP_MEMORY_SCOPE_AGENT); }
; __device__ __forceinline__ float dot4(const f32x4 a) { return (a[0] * a[0] + a[1] * a[1]) + (a[2] * a[2] + a[3] * a[3]); }
;     __device__ __forceinline__ void operator()(const f32x4 (&acc)[2][2][4][2], const Unit& u, int wr, int wc, int fr, int fq) const {
;     ...
;             for (int m = 0; m < 4; ++m) { const int row = row0 + ai * HALF + m * 16; const size_t off = (size_t)row * 2048 + col0; float sq = 0.f;
; #pragma unroll
;                 for (int bj = 0; bj < 2; ++bj) {
;                     const f32x4 x0 = __builtin_nontemporal_load((const f32x4*)(xin + off + bj * HALF)), x1 = __builtin_nontemporal_load((const f32x4*)(xin + off + bj * HALF + 4));
;                     const f32x4 v0 = x0 + acc[ai][bj][m][0] * alpha, v1 = x1 + acc[ai][bj][m][1] * alpha;
;                     __builtin_nontemporal_store(v0, (f32x4*)(xout + off + bj * HALF)); __builtin_nontemporal_store(v1, (f32x4*)(xout + off + bj * HALF + 4));
;                     if (WRITE_XB) *(u32x4*)(xb + off + bj * HALF) = pack8(v0, v1); sq += dot4(v0) + dot4(v1); }
;                 sq += __shfl_xor(sq, 16); sq += __shfl_xor(sq, 32);
;                 if (fq == 0) ss_add(ssout + row, sq); }
.LBB0_1482:
	s_or_b64 exec, exec, s[48:49]
	v_or_b32_e32 v96, 32, v146
	s_waitcnt lgkmcnt(0)
	v_ashrrev_i32_e32 v97, 31, v96
	v_lshlrev_b64 v[98:99], 11, v[96:97]
	v_lshl_add_u64 v[106:107], v[98:99], 0, v[144:145]
	v_lshl_add_u64 v[108:109], v[106:107], 2, s[28:29]
	global_load_dwordx4 v[98:101], v[108:109], off nt
	global_load_dwordx4 v[102:105], v[108:109], off offset:16 nt
	global_load_dwordx4 v[176:179], v[108:109], off offset:512 nt
	global_load_dwordx4 v[180:183], v[108:109], off offset:528 nt
	v_lshl_add_u64 v[106:107], v[106:107], 1, s[46:47]
	s_waitcnt vmcnt(3)
	v_pk_fma_f32 v[94:95], v[94:95], 0.5, v[100:101] op_sel_hi:[1,0,1]
	v_pk_fma_f32 v[92:93], v[92:93], 0.5, v[98:99] op_sel_hi:[1,0,1]
	s_waitcnt vmcnt(2)
	v_pk_fma_f32 v[90:91], v[90:91], 0.5, v[104:105] op_sel_hi:[1,0,1]
	v_pk_fma_f32 v[88:89], v[88:89], 0.5, v[102:103] op_sel_hi:[1,0,1]
	v_cvt_pk_bf16_f32 v98, v92, v93
	v_cvt_pk_bf16_f32 v99, v94, v95
	v_cvt_pk_bf16_f32 v100, v88, v89
	v_cvt_pk_bf16_f32 v101, v90, v91
	global_store_dwordx4 v[108:109], v[92:95], off nt
	global_store_dwordx4 v[108:109], v[88:91], off offset:16 nt
	global_store_dwordx4 v[106:107], v[98:101], off
	s_nop 1
	v_mul_f32_e32 v93, v93, v93
	v_mul_f32_e32 v95, v95, v95
	v_mul_f32_e32 v89, v89, v89
	v_mul_f32_e32 v91, v91, v91
	v_fmac_f32_e32 v93, v92, v92
	v_fmac_f32_e32 v95, v94, v94
	v_fmac_f32_e32 v89, v88, v88
	v_fmac_f32_e32 v91, v90, v90
	v_add_f32_e32 v88, v93, v95
	v_add_f32_e32 v89, v89, v91
	v_add_f32_e32 v92, v88, v89
	s_waitcnt vmcnt(4)
	v_pk_fma_f32 v[86:87], v[86:87], 0.5, v[178:179] op_sel_hi:[1,0,1]
	v_pk_fma_f32 v[84:85], v[84:85], 0.5, v[176:177] op_sel_hi:[1,0,1]
	s_waitcnt vmcnt(3)
	v_pk_fma_f32 v[90:91], v[82:83], 0.5, v[182:183] op_sel_hi:[1,0,1]
	v_pk_fma_f32 v[88:89], v[80:81], 0.5, v[180:181] op_sel_hi:[1,0,1]
	v_mul_f32_e32 v80, v85, v85
	v_mul_f32_e32 v81, v87, v87
	v_mul_f32_e32 v82, v89, v89
	v_mul_f32_e32 v83, v91, v91
	v_fmac_f32_e32 v80, v84, v84
	v_fmac_f32_e32 v81, v86, v86
	v_fmac_f32_e32 v82, v88, v88
	v_fmac_f32_e32 v83, v90, v90
	v_add_f32_e32 v80, v80, v81
	v_add_f32_e32 v81, v82, v83
	v_add_f32_e32 v80, v80, v81
	v_add_f32_e32 v80, v92, v80
	ds_bpermute_b32 v81, v120, v80
	global_store_dwordx4 v[108:109], v[84:87], off offset:512 nt
	global_store_dwordx4 v[108:109], v[88:91], off offset:528 nt
	v_cvt_pk_bf16_f32 v82, v84, v85
	v_cvt_pk_bf16_f32 v83, v86, v87
	v_cvt_pk_bf16_f32 v84, v88, v89
	s_waitcnt lgkmcnt(0)
	v_add_f32_e32 v80, v80, v81
	ds_bpermute_b32 v81, v114, v80
	v_cvt_pk_bf16_f32 v85, v90, v91
	global_store_dwordx4 v[106:107], v[82:85], off offset:256
	s_and_saveexec_b64 s[48:49], s[2:3]
	s_cbranch_execz .LBB0_1484
	s_waitcnt lgkmcnt(0)
	v_add_f32_e32 v80, v80, v81
	v_mul_f32_e32 v80, 0x4b800000, v80
	v_trunc_f32_e32 v80, v80
	v_mul_f32_e32 v81, 0x2f800000, v80
	v_floor_f32_e32 v81, v81
	v_fmac_f32_e32 v80, 0xcf800000, v81
	v_cvt_u32_f32_e32 v80, v80
	v_cvt_u32_f32_e32 v81, v81
	v_lshl_add_u64 v[82:83], v[96:97], 3, s[18:19]
	global_atomic_add_x2 v[82:83], v[80:81], off
.LBB0_1484:
	s_or_b64 exec, exec, s[48:49]
	v_or_b32_e32 v80, 48, v146
	s_waitcnt lgkmcnt(0)
	v_ashrrev_i32_e32 v81, 31, v80
	v_lshlrev_b64 v[82:83], 11, v[80:81]
	v_lshl_add_u64 v[90:91], v[82:83], 0, v[144:145]
	v_lshl_add_u64 v[92:93], v[90:91], 2, s[28:29]
	global_load_dwordx4 v[82:85], v[92:93], off nt
	global_load_dwordx4 v[86:89], v[92:93], off offset:16 nt
	global_load_dwordx4 v[176:179], v[92:93], off offset:512 nt
	global_load_dwordx4 v[180:183], v[92:93], off offset:528 nt
	v_lshl_add_u64 v[90:91], v[90:91], 1, s[46:47]
	s_waitcnt vmcnt(3)
	v_pk_fma_f32 v[78:79], v[78:79], 0.5, v[84:85] op_sel_hi:[1,0,1]
	v_pk_fma_f32 v[76:77], v[76:77], 0.5, v[82:83] op_sel_hi:[1,0,1]
	s_waitcnt vmcnt(2)
	v_pk_fma_f32 v[74:75], v[74:75], 0.5, v[88:89] op_sel_hi:[1,0,1]
	v_pk_fma_f32 v[72:73], v[72:73], 0.5, v[86:87] op_sel_hi:[1,0,1]
	v_cvt_pk_bf16_f32 v82, v76, v77
	v_cvt_pk_bf16_f32 v83, v78, v79
	v_cvt_pk_bf16_f32 v84, v72, v73
	v_cvt_pk_bf16_f32 v85, v74, v75
	global_store_dwordx4 v[92:93], v[76:79], off nt
	global_store_dwordx4 v[92:93], v[72:75], off offset:16 nt
	global_store_dwordx4 v[90:91], v[82:85], off
	s_nop 1
	v_mul_f32_e32 v77, v77, v77
	v_mul_f32_e32 v79, v79, v79
	v_mul_f32_e32 v73, v73, v73
	v_mul_f32_e32 v75, v75, v75
	v_fmac_f32_e32 v77, v76, v76
	v_fmac_f32_e32 v79, v78, v78
	v_fmac_f32_e32 v73, v72, v72
	v_fmac_f32_e32 v75, v74, v74
	v_add_f32_e32 v72, v77, v79
	v_add_f32_e32 v73, v73, v75
	v_add_f32_e32 v76, v72, v73
	s_waitcnt vmcnt(4)
	v_pk_fma_f32 v[70:71], v[70:71], 0.5, v[178:179] op_sel_hi:[1,0,1]
	v_pk_fma_f32 v[68:69], v[68:69], 0.5, v[176:177] op_sel_hi:[1,0,1]
	s_waitcnt vmcnt(3)
	v_pk_fma_f32 v[74:75], v[66:67], 0.5, v[182:183] op_sel_hi:[1,0,1]
	v_pk_fma_f32 v[72:73], v[64:65], 0.5, v[180:181] op_sel_hi:[1,0,1]
	v_mul_f32_e32 v64, v69, v69
	v_mul_f32_e32 v65, v71, v71
	v_mul_f32_e32 v66, v73, v73
	v_mul_f32_e32 v67, v75, v75
	v_fmac_f32_e32 v64, v68, v68
	v_fmac_f32_e32 v65, v70, v70
	v_fmac_f32_e32 v66, v72, v72
	v_fmac_f32_e32 v67, v74, v74
	v_add_f32_e32 v64, v64, v65
	v_add_f32_e32 v65, v66, v67
	v_add_f32_e32 v64, v64, v65
	v_add_f32_e32 v64, v76, v64
	ds_bpermute_b32 v65, v120, v64
	global_store_dwordx4 v[92:93], v[68:71], off offset:512 nt
	global_store_dwordx4 v[92:93], v[72:75], off offset:528 nt
	v_cvt_pk_bf16_f32 v66, v68, v69
	v_cvt_pk_bf16_f32 v67, v70, v71
	v_cvt_pk_bf16_f32 v68, v72, v73
	s_waitcnt lgkmcnt(0)
	v_add_f32_e32 v64, v64, v65
	ds_bpermute_b32 v65, v114, v64
	v_cvt_pk_bf16_f32 v69, v74, v75
	global_store_dwordx4 v[90:91], v[66:69], off offset:256
	s_and_saveexec_b64 s[48:49], s[2:3]
	s_cbranch_execz .LBB0_1486
	s_waitcnt lgkmcnt(0)
	v_add_f32_e32 v64, v64, v65
	v_mul_f32_e32 v64, 0x4b800000, v64
	v_trunc_f32_e32 v64, v64
	v_mul_f32_e32 v65, 0x2f800000, v64
	v_floor_f32_e32 v65, v65
	v_fmac_f32_e32 v64, 0xcf800000, v65
	v_cvt_u32_f32_e32 v64, v64
	v_cvt_u32_f32_e32 v65, v65
	v_lshl_add_u64 v[66:67], v[80:81], 3, s[18:19]
	global_atomic_add_x2 v[66:67], v[64:65], off
; __device__ __forceinline__ u32x4 pack8(const f32x4 a, const f32x4 b) { u32x4 w; w.x = cvt_pk_bf16(a[0], a[1]); w.y = cvt_pk_bf16(a[2], a[3]); w.z = cvt_pk_bf16(b[0], b[1]); w.w = cvt_pk_bf16(b[2], b[3]); return w; }
; __device__ __forceinline__ void ss_add(ssq_t* p, float sq) { __hip_atomic_fetch_add(p, (ssq_t)(sq * 16777216.0f), __ATOMIC_RELAXED, __HIP_MEMORY_SCOPE_AGENT); }
; __device__ __forceinline__ float dot4(const f32x4 a) { return (a[0] * a[0] + a[1] * a[1]) + (a[2] * a[2] + a[3] * a[3]); }
;     __device__ __forceinline__ void operator()(const f32x4 (&acc)[2][2][4][2], const Unit& u, int wr, int wc, int fr, int fq) const {
;     ...
;             for (int m = 0; m < 4; ++m) { const int row = row0 + ai * HALF + m * 16; const size_t off = (size_t)row * 2048 + col0; float sq = 0.f;
; #pragma unroll
;                 for (int bj = 0; bj < 2; ++bj) {
;                     const f32x4 x0 = __builtin_nontemporal_load((const f32x4*)(xin + off + bj * HALF)), x1 = __builtin_nontemporal_load((const f32x4*)(xin + off + bj * HALF + 4));
;                     const f32x4 v0 = x0 + acc[ai][bj][m][0] * alpha, v1 = x1 + acc[ai][bj][m][1] * alpha;
;                     __builtin_nontemporal_store(v0, (f32x4*)(xout + off + bj * HALF)); __builtin_nontemporal_store(v1, (f32x4*)(xout + off + bj * HALF + 4));
;                     if (WRITE_XB) *(u32x4*)(xb + off + bj * HALF) = pack8(v0, v1); sq += dot4(v0) + dot4(v1); }
;                 sq += __shfl_xor(sq, 16); sq += __shfl_xor(sq, 32);
;                 if (fq == 0) ss_add(ssout + row, sq); }
.LBB0_1486:
	s_or_b64 exec, exec, s[48:49]
	v_add_u32_e32 v64, 0x80, v146
	s_waitcnt lgkmcnt(0)
	v_ashrrev_i32_e32 v65, 31, v64
	v_lshlrev_b64 v[66:67], 11, v[64:65]
	v_lshl_add_u64 v[74:75], v[66:67], 0, v[144:145]
	v_lshl_add_u64 v[76:77], v[74:75], 2, s[28:29]
	global_load_dwordx4 v[66:69], v[76:77], off nt
	global_load_dwordx4 v[70:73], v[76:77], off offset:16 nt
	global_load_dwordx4 v[176:179], v[76:77], off offset:512 nt
	global_load_dwordx4 v[180:183], v[76:77], off offset:528 nt
	v_lshl_add_u64 v[74:75], v[74:75], 1, s[46:47]
	s_waitcnt vmcnt(3)
	v_pk_fma_f32 v[62:63], v[62:63], 0.5, v[68:69] op_sel_hi:[1,0,1]
	v_pk_fma_f32 v[60:61], v[60:61], 0.5, v[66:67] op_sel_hi:[1,0,1]
	s_waitcnt vmcnt(2)
	v_pk_fma_f32 v[58:59], v[58:59], 0.5, v[72:73] op_sel_hi:[1,0,1]
	v_pk_fma_f32 v[56:57], v[56:57], 0.5, v[70:71] op_sel_hi:[1,0,1]
	v_cvt_pk_bf16_f32 v66, v60, v61
	v_cvt_pk_bf16_f32 v67, v62, v63
	v_cvt_pk_bf16_f32 v68, v56, v57
	v_cvt_pk_bf16_f32 v69, v58, v59
	global_store_dwordx4 v[76:77], v[60:63], off nt
	global_store_dwordx4 v[76:77], v[56:59], off offset:16 nt
	global_store_dwordx4 v[74:75], v[66:69], off
	s_nop 1
	v_mul_f32_e32 v61, v61, v61
	v_mul_f32_e32 v63, v63, v63
	v_mul_f32_e32 v57, v57, v57
	v_mul_f32_e32 v59, v59, v59
	v_fmac_f32_e32 v61, v60, v60
	v_fmac_f32_e32 v63, v62, v62
	v_fmac_f32_e32 v57, v56, v56
	v_fmac_f32_e32 v59, v58, v58
	v_add_f32_e32 v56, v61, v63
	v_add_f32_e32 v57, v57, v59
	v_add_f32_e32 v60, v56, v57
	s_waitcnt vmcnt(4)
	v_pk_fma_f32 v[54:55], v[54:55], 0.5, v[178:179] op_sel_hi:[1,0,1]
	v_pk_fma_f32 v[52:53], v[52:53], 0.5, v[176:177] op_sel_hi:[1,0,1]
	s_waitcnt vmcnt(3)
	v_pk_fma_f32 v[58:59], v[50:51], 0.5, v[182:183] op_sel_hi:[1,0,1]
	v_pk_fma_f32 v[56:57], v[48:49], 0.5, v[180:181] op_sel_hi:[1,0,1]
	v_mul_f32_e32 v48, v53, v53
	v_mul_f32_e32 v49, v55, v55
	v_mul_f32_e32 v50, v57, v57
	v_mul_f32_e32 v51, v59, v59
	v_fmac_f32_e32 v48, v52, v52
	v_fmac_f32_e32 v49, v54, v54
	v_fmac_f32_e32 v50, v56, v56
	v_fmac_f32_e32 v51, v58, v58
	v_add_f32_e32 v48, v48, v49
	v_add_f32_e32 v49, v50, v51
	v_add_f32_e32 v48, v48, v49
	v_add_f32_e32 v48, v60, v48
	ds_bpermute_b32 v49, v120, v48
	global_store_dwordx4 v[76:77], v[52:55], off offset:512 nt
	global_store_dwordx4 v[76:77], v[56:59], off offset:528 nt
	v_cvt_pk_bf16_f32 v50, v52, v53
	v_cvt_pk_bf16_f32 v51, v54, v55
	v_cvt_pk_bf16_f32 v52, v56, v57
	s_waitcnt lgkmcnt(0)
	v_add_f32_e32 v48, v48, v49
	ds_bpermute_b32 v49, v114, v48
	v_cvt_pk_bf16_f32 v53, v58, v59
	global_store_dwordx4 v[74:75], v[50:53], off offset:256
	s_and_saveexec_b64 s[48:49], s[2:3]
	s_cbranch_execz .LBB0_1488
	s_waitcnt lgkmcnt(0)
	v_add_f32_e32 v48, v48, v49
	v_mul_f32_e32 v48, 0x4b800000, v48
	v_trunc_f32_e32 v48, v48
	v_mul_f32_e32 v49, 0x2f800000, v48
	v_floor_f32_e32 v49, v49
	v_fmac_f32_e32 v48, 0xcf800000, v49
	v_cvt_u32_f32_e32 v48, v48
	v_cvt_u32_f32_e32 v49, v49
	v_lshl_add_u64 v[50:51], v[64:65], 3, s[18:19]
	global_atomic_add_x2 v[50:51], v[48:49], off
.LBB0_1488:
	s_or_b64 exec, exec, s[48:49]
	v_add_u32_e32 v48, 0x90, v146
	s_waitcnt lgkmcnt(0)
	v_ashrrev_i32_e32 v49, 31, v48
	v_lshlrev_b64 v[50:51], 11, v[48:49]
	v_lshl_add_u64 v[58:59], v[50:51], 0, v[144:145]
	v_lshl_add_u64 v[60:61], v[58:59], 2, s[28:29]
	global_load_dwordx4 v[50:53], v[60:61], off nt
	global_load_dwordx4 v[54:57], v[60:61], off offset:16 nt
	global_load_dwordx4 v[176:179], v[60:61], off offset:512 nt
	global_load_dwordx4 v[180:183], v[60:61], off offset:528 nt
	v_lshl_add_u64 v[58:59], v[58:59], 1, s[46:47]
	s_waitcnt vmcnt(3)
	v_pk_fma_f32 v[46:47], v[46:47], 0.5, v[52:53] op_sel_hi:[1,0,1]
	v_pk_fma_f32 v[44:45], v[44:45], 0.5, v[50:51] op_sel_hi:[1,0,1]
	s_waitcnt vmcnt(2)
	v_pk_fma_f32 v[42:43], v[42:43], 0.5, v[56:57] op_sel_hi:[1,0,1]
	v_pk_fma_f32 v[40:41], v[40:41], 0.5, v[54:55] op_sel_hi:[1,0,1]
	v_cvt_pk_bf16_f32 v50, v44, v45
	v_cvt_pk_bf16_f32 v51, v46, v47
	v_cvt_pk_bf16_f32 v52, v40, v41
	v_cvt_pk_bf16_f32 v53, v42, v43
	global_store_dwordx4 v[60:61], v[44:47], off nt
	global_store_dwordx4 v[60:61], v[40:43], off offset:16 nt
	global_store_dwordx4 v[58:59], v[50:53], off
	s_nop 1
	v_mul_f32_e32 v45, v45, v45
	v_mul_f32_e32 v47, v47, v47
	v_mul_f32_e32 v41, v41, v41
	v_mul_f32_e32 v43, v43, v43
	v_fmac_f32_e32 v45, v44, v44
	v_fmac_f32_e32 v47, v46, v46
	v_fmac_f32_e32 v41, v40, v40
	v_fmac_f32_e32 v43, v42, v42
	v_add_f32_e32 v40, v45, v47
	v_add_f32_e32 v41, v41, v43
	v_add_f32_e32 v44, v40, v41
	s_waitcnt vmcnt(4)
	v_pk_fma_f32 v[38:39], v[38:39], 0.5, v[178:179] op_sel_hi:[1,0,1]
	v_pk_fma_f32 v[36:37], v[36:37], 0.5, v[176:177] op_sel_hi:[1,0,1]
	s_waitcnt vmcnt(3)
	v_pk_fma_f32 v[42:43], v[34:35], 0.5, v[182:183] op_sel_hi:[1,0,1]
	v_pk_fma_f32 v[40:41], v[32:33], 0.5, v[180:181] op_sel_hi:[1,0,1]
	v_mul_f32_e32 v32, v37, v37
	v_mul_f32_e32 v33, v39, v39
	v_mul_f32_e32 v34, v41, v41
	v_mul_f32_e32 v35, v43, v43
	v_fmac_f32_e32 v32, v36, v36
	v_fmac_f32_e32 v33, v38, v38
	v_fmac_f32_e32 v34, v40, v40
	v_fmac_f32_e32 v35, v42, v42
	v_add_f32_e32 v32, v32, v33
	v_add_f32_e32 v33, v34, v35
	v_add_f32_e32 v32, v32, v33
	v_add_f32_e32 v32, v44, v32
	ds_bpermute_b32 v33, v120, v32
	global_store_dwordx4 v[60:61], v[36:39], off offset:512 nt
	global_store_dwordx4 v[60:61], v[40:43], off offset:528 nt
	v_cvt_pk_bf16_f32 v34, v36, v37
	v_cvt_pk_bf16_f32 v35, v38, v39
	v_cvt_pk_bf16_f32 v36, v40, v41
	s_waitcnt lgkmcnt(0)
	v_add_f32_e32 v32, v32, v33
	ds_bpermute_b32 v33, v114, v32
	v_cvt_pk_bf16_f32 v37, v42, v43
	global_store_dwordx4 v[58:59], v[34:37], off offset:256
	s_and_saveexec_b64 s[48:49], s[2:3]
	s_cbranch_execz .LBB0_1490
	s_waitcnt lgkmcnt(0)
	v_add_f32_e32 v32, v32, v33
	v_mul_f32_e32 v32, 0x4b800000, v32
	v_trunc_f32_e32 v32, v32
	v_mul_f32_e32 v33, 0x2f800000, v32
	v_floor_f32_e32 v33, v33
	v_fmac_f32_e32 v32, 0xcf800000, v33
	v_cvt_u32_f32_e32 v32, v32
	v_cvt_u32_f32_e32 v33, v33
	v_lshl_add_u64 v[34:35], v[48:49], 3, s[18:19]
	global_atomic_add_x2 v[34:35], v[32:33], off
; __device__ __forceinline__ u32x4 pack8(const f32x4 a, const f32x4 b) { u32x4 w; w.x = cvt_pk_bf16(a[0], a[1]); w.y = cvt_pk_bf16(a[2], a[3]); w.z = cvt_pk_bf16(b[0], b[1]); w.w = cvt_pk_bf16(b[2], b[3]); return w; }
; __device__ __forceinline__ void ss_add(ssq_t* p, float sq) { __hip_atomic_fetch_add(p, (ssq_t)(sq * 16777216.0f), __ATOMIC_RELAXED, __HIP_MEMORY_SCOPE_AGENT); }
; __device__ __forceinline__ float dot4(const f32x4 a) { return (a[0] * a[0] + a[1] * a[1]) + (a[2] * a[2] + a[3] * a[3]); }
;     __device__ __forceinline__ void operator()(const f32x4 (&acc)[2][2][4][2], const Unit& u, int wr, int wc, int fr, int fq) const {
;     ...
;             for (int m = 0; m < 4; ++m) { const int row = row0 + ai * HALF + m * 16; const size_t off = (size_t)row * 2048 + col0; float sq = 0.f;
; #pragma unroll
;                 for (int bj = 0; bj < 2; ++bj) {
;                     const f32x4 x0 = __builtin_nontemporal_load((const f32x4*)(xin + off + bj * HALF)), x1 = __builtin_nontemporal_load((const f32x4*)(xin + off + bj * HALF + 4));
;                     const f32x4 v0 = x0 + acc[ai][bj][m][0] * alpha, v1 = x1 + acc[ai][bj][m][1] * alpha;
;                     __builtin_nontemporal_store(v0, (f32x4*)(xout + off + bj * HALF)); __builtin_nontemporal_store(v1, (f32x4*)(xout + off + bj * HALF + 4));
;                     if (WRITE_XB) *(u32x4*)(xb + off + bj * HALF) = pack8(v0, v1); sq += dot4(v0) + dot4(v1); }
;                 sq += __shfl_xor(sq, 16); sq += __shfl_xor(sq, 32);
;                 if (fq == 0) ss_add(ssout + row, sq); }
.LBB0_1490:
	s_or_b64 exec, exec, s[48:49]
	v_add_u32_e32 v32, 0xa0, v146
	s_waitcnt lgkmcnt(0)
	v_ashrrev_i32_e32 v33, 31, v32
	v_lshlrev_b64 v[34:35], 11, v[32:33]
	v_lshl_add_u64 v[42:43], v[34:35], 0, v[144:145]
	v_lshl_add_u64 v[44:45], v[42:43], 2, s[28:29]
	global_load_dwordx4 v[34:37], v[44:45], off nt
	global_load_dwordx4 v[38:41], v[44:45], off offset:16 nt
	global_load_dwordx4 v[176:179], v[44:45], off offset:512 nt
	global_load_dwordx4 v[180:183], v[44:45], off offset:528 nt
	v_lshl_add_u64 v[42:43], v[42:43], 1, s[46:47]
	s_waitcnt vmcnt(3)
	v_pk_fma_f32 v[30:31], v[30:31], 0.5, v[36:37] op_sel_hi:[1,0,1]
	v_pk_fma_f32 v[28:29], v[28:29], 0.5, v[34:35] op_sel_hi:[1,0,1]
	s_waitcnt vmcnt(2)
	v_pk_fma_f32 v[26:27], v[26:27], 0.5, v[40:41] op_sel_hi:[1,0,1]
	v_pk_fma_f32 v[24:25], v[24:25], 0.5, v[38:39] op_sel_hi:[1,0,1]
	v_cvt_pk_bf16_f32 v34, v28, v29
	v_cvt_pk_bf16_f32 v35, v30, v31
	v_cvt_pk_bf16_f32 v36, v24, v25
	v_cvt_pk_bf16_f32 v37, v26, v27
	global_store_dwordx4 v[44:45], v[28:31], off nt
	global_store_dwordx4 v[44:45], v[24:27], off offset:16 nt
	global_store_dwordx4 v[42:43], v[34:37], off
	s_nop 1
	v_mul_f32_e32 v29, v29, v29
	v_mul_f32_e32 v31, v31, v31
	v_mul_f32_e32 v25, v25, v25
	v_mul_f32_e32 v27, v27, v27
	v_fmac_f32_e32 v29, v28, v28
	v_fmac_f32_e32 v31, v30, v30
	v_fmac_f32_e32 v25, v24, v24
	v_fmac_f32_e32 v27, v26, v26
	v_add_f32_e32 v24, v29, v31
	v_add_f32_e32 v25, v25, v27
	v_add_f32_e32 v28, v24, v25
	s_waitcnt vmcnt(4)
	v_pk_fma_f32 v[22:23], v[22:23], 0.5, v[178:179] op_sel_hi:[1,0,1]
	v_pk_fma_f32 v[20:21], v[20:21], 0.5, v[176:177] op_sel_hi:[1,0,1]
	s_waitcnt vmcnt(3)
	v_pk_fma_f32 v[26:27], v[18:19], 0.5, v[182:183] op_sel_hi:[1,0,1]
	v_pk_fma_f32 v[24:25], v[16:17], 0.5, v[180:181] op_sel_hi:[1,0,1]
	v_mul_f32_e32 v16, v21, v21
	v_mul_f32_e32 v17, v23, v23
	v_mul_f32_e32 v18, v25, v25
	v_mul_f32_e32 v19, v27, v27
	v_fmac_f32_e32 v16, v20, v20
	v_fmac_f32_e32 v17, v22, v22
	v_fmac_f32_e32 v18, v24, v24
	v_fmac_f32_e32 v19, v26, v26
	v_add_f32_e32 v16, v16, v17
	v_add_f32_e32 v17, v18, v19
	v_add_f32_e32 v16, v16, v17
	v_add_f32_e32 v16, v28, v16
	ds_bpermute_b32 v17, v120, v16
	global_store_dwordx4 v[44:45], v[20:23], off offset:512 nt
	global_store_dwordx4 v[44:45], v[24:27], off offset:528 nt
	v_cvt_pk_bf16_f32 v18, v20, v21
	v_cvt_pk_bf16_f32 v19, v22, v23
	v_cvt_pk_bf16_f32 v20, v24, v25
	s_waitcnt lgkmcnt(0)
	v_add_f32_e32 v16, v16, v17
	ds_bpermute_b32 v17, v114, v16
	v_cvt_pk_bf16_f32 v21, v26, v27
	global_store_dwordx4 v[42:43], v[18:21], off offset:256
	s_and_saveexec_b64 s[48:49], s[2:3]
	s_cbranch_execz .LBB0_1492
	s_waitcnt lgkmcnt(0)
	v_add_f32_e32 v16, v16, v17
	v_mul_f32_e32 v16, 0x4b800000, v16
	v_trunc_f32_e32 v16, v16
	v_mul_f32_e32 v17, 0x2f800000, v16
	v_floor_f32_e32 v17, v17
	v_fmac_f32_e32 v16, 0xcf800000, v17
	v_cvt_u32_f32_e32 v16, v16
	v_cvt_u32_f32_e32 v17, v17
	v_lshl_add_u64 v[18:19], v[32:33], 3, s[18:19]
	global_atomic_add_x2 v[18:19], v[16:17], off
.LBB0_1492:
	s_or_b64 exec, exec, s[48:49]
	v_add_u32_e32 v16, 0xb0, v146
	s_waitcnt lgkmcnt(0)
	v_ashrrev_i32_e32 v17, 31, v16
	v_lshlrev_b64 v[18:19], 11, v[16:17]
	v_lshl_add_u64 v[26:27], v[18:19], 0, v[144:145]
	v_lshl_add_u64 v[28:29], v[26:27], 2, s[28:29]
	global_load_dwordx4 v[18:21], v[28:29], off nt
	global_load_dwordx4 v[22:25], v[28:29], off offset:16 nt
	global_load_dwordx4 v[176:179], v[28:29], off offset:512 nt
	global_load_dwordx4 v[180:183], v[28:29], off offset:528 nt
	v_lshl_add_u64 v[26:27], v[26:27], 1, s[46:47]
	s_waitcnt vmcnt(3)
	v_pk_fma_f32 v[14:15], v[14:15], 0.5, v[20:21] op_sel_hi:[1,0,1]
	v_pk_fma_f32 v[12:13], v[12:13], 0.5, v[18:19] op_sel_hi:[1,0,1]
	s_waitcnt vmcnt(2)
	v_pk_fma_f32 v[10:11], v[10:11], 0.5, v[24:25] op_sel_hi:[1,0,1]
	v_pk_fma_f32 v[8:9], v[8:9], 0.5, v[22:23] op_sel_hi:[1,0,1]
	v_cvt_pk_bf16_f32 v18, v12, v13
	v_cvt_pk_bf16_f32 v19, v14, v15
	v_cvt_pk_bf16_f32 v20, v8, v9
	v_cvt_pk_bf16_f32 v21, v10, v11
	global_store_dwordx4 v[28:29], v[12:15], off nt
	global_store_dwordx4 v[28:29], v[8:11], off offset:16 nt
	global_store_dwordx4 v[26:27], v[18:21], off
	s_nop 1
	v_mul_f32_e32 v13, v13, v13
	v_mul_f32_e32 v15, v15, v15
	v_mul_f32_e32 v9, v9, v9
	v_mul_f32_e32 v11, v11, v11
	v_fmac_f32_e32 v13, v12, v12
	v_fmac_f32_e32 v15, v14, v14
	v_fmac_f32_e32 v9, v8, v8
	v_fmac_f32_e32 v11, v10, v10
	v_add_f32_e32 v8, v13, v15
	v_add_f32_e32 v9, v9, v11
	v_add_f32_e32 v12, v8, v9
	s_waitcnt vmcnt(4)
	v_pk_fma_f32 v[6:7], v[6:7], 0.5, v[178:179] op_sel_hi:[1,0,1]
	v_pk_fma_f32 v[4:5], v[4:5], 0.5, v[176:177] op_sel_hi:[1,0,1]
	s_waitcnt vmcnt(3)
	v_pk_fma_f32 v[10:11], v[2:3], 0.5, v[182:183] op_sel_hi:[1,0,1]
	v_pk_fma_f32 v[8:9], v[0:1], 0.5, v[180:181] op_sel_hi:[1,0,1]
	v_mul_f32_e32 v0, v5, v5
	v_mul_f32_e32 v1, v7, v7
	v_mul_f32_e32 v2, v9, v9
	v_mul_f32_e32 v3, v11, v11
	v_fmac_f32_e32 v0, v4, v4
	v_fmac_f32_e32 v1, v6, v6
	v_fmac_f32_e32 v2, v8, v8
	v_fmac_f32_e32 v3, v10, v10
	v_add_f32_e32 v0, v0, v1
	v_add_f32_e32 v1, v2, v3
	v_add_f32_e32 v0, v0, v1
	v_add_f32_e32 v0, v12, v0
	ds_bpermute_b32 v1, v120, v0
	global_store_dwordx4 v[28:29], v[4:7], off offset:512 nt
	global_store_dwordx4 v[28:29], v[8:11], off offset:528 nt
	v_cvt_pk_bf16_f32 v2, v4, v5
	v_cvt_pk_bf16_f32 v3, v6, v7
	v_cvt_pk_bf16_f32 v4, v8, v9
	s_waitcnt lgkmcnt(0)
	v_add_f32_e32 v0, v0, v1
	ds_bpermute_b32 v1, v114, v0
	v_cvt_pk_bf16_f32 v5, v10, v11
	global_store_dwordx4 v[26:27], v[2:5], off offset:256
	s_and_saveexec_b64 s[48:49], s[2:3]
	s_cbranch_execz .LBB0_1494
	s_waitcnt lgkmcnt(0)
	v_add_f32_e32 v0, v0, v1
	v_mul_f32_e32 v0, 0x4b800000, v0
	v_trunc_f32_e32 v0, v0
	v_mul_f32_e32 v1, 0x2f800000, v0
	v_floor_f32_e32 v1, v1
	v_fmac_f32_e32 v0, 0xcf800000, v1
	v_cvt_u32_f32_e32 v0, v0
	v_cvt_u32_f32_e32 v1, v1
	v_lshl_add_u64 v[2:3], v[16:17], 3, s[18:19]
	global_atomic_add_x2 v[2:3], v[0:1], off

; __device__ __forceinline__ u32x4 pack8(const f32x4 a, const f32x4 b) { u32x4 w; w.x = cvt_pk_bf16(a[0], a[1]); w.y = cvt_pk_bf16(a[2], a[3]); w.z = cvt_pk_bf16(b[0], b[1]); w.w = cvt_pk_bf16(b[2], b[3]); return w; }
; __device__ __forceinline__ void ss_add(ssq_t* p, float sq) { __hip_atomic_fetch_add(p, (ssq_t)(sq * 16777216.0f), __ATOMIC_RELAXED, __HIP_MEMORY_SCOPE_AGENT); }
; __device__ __forceinline__ float dot4(const f32x4 a) { return (a[0] * a[0] + a[1] * a[1]) + (a[2] * a[2] + a[3] * a[3]); }
;     __device__ __forceinline__ void operator()(const f32x4 (&acc)[2][2][4][2], const Unit& u, int wr, int wc, int fr, int fq) const {
;     ...
;             for (int m = 0; m < 4; ++m) { const int row = row0 + ai * HALF + m * 16; const size_t off = (size_t)row * 2048 + col0; float sq = 0.f;
; #pragma unroll
;                 for (int bj = 0; bj < 2; ++bj) {
;                     const f32x4 x0 = __builtin_nontemporal_load((const f32x4*)(xin + off + bj * HALF)), x1 = __builtin_nontemporal_load((const f32x4*)(xin + off + bj * HALF + 4));
;                     const f32x4 v0 = x0 + acc[ai][bj][m][0] * alpha, v1 = x1 + acc[ai][bj][m][1] * alpha;
;                     __builtin_nontemporal_store(v0, (f32x4*)(xout + off + bj * HALF)); __builtin_nontemporal_store(v1, (f32x4*)(xout + off + bj * HALF + 4));
;                     if (WRITE_XB) *(u32x4*)(xb + off + bj * HALF) = pack8(v0, v1); sq += dot4(v0) + dot4(v1); }
;                 sq += __shfl_xor(sq, 16); sq += __shfl_xor(sq, 32);
;                 if (fq == 0) ss_add(ssout + row, sq); }
.LBB0_2085:
	v_lshl_add_u32 v146, s24, 8, v148
	v_lshl_add_u32 v144, s36, 8, v150
	v_ashrrev_i32_e32 v147, 31, v146
	v_ashrrev_i32_e32 v145, 31, v144
	v_lshlrev_b64 v[156:157], 11, v[146:147]
	v_lshl_add_u64 v[164:165], v[156:157], 0, v[144:145]
	v_lshl_add_u64 v[168:169], v[164:165], 2, s[28:29]
	global_load_dwordx4 v[156:159], v[168:169], off nt
	global_load_dwordx4 v[160:163], v[168:169], off offset:16 nt
	global_load_dwordx4 v[176:179], v[168:169], off offset:512 nt
	global_load_dwordx4 v[180:183], v[168:169], off offset:528 nt
	v_lshl_add_u64 v[170:171], v[164:165], 1, s[46:47]
	s_waitcnt vmcnt(2)
	v_pk_add_f32 v[126:127], v[126:127], v[158:159]
	v_pk_add_f32 v[124:125], v[124:125], v[156:157]
	v_pk_add_f32 v[158:159], v[122:123], v[162:163]
	v_pk_add_f32 v[156:157], v[120:121], v[160:161]
	v_cvt_pk_bf16_f32 v120, v124, v125
	v_cvt_pk_bf16_f32 v121, v126, v127
	v_cvt_pk_bf16_f32 v122, v156, v157
	v_cvt_pk_bf16_f32 v123, v158, v159
	global_store_dwordx4 v[168:169], v[124:127], off nt
	global_store_dwordx4 v[168:169], v[156:159], off offset:16 nt
	global_store_dwordx4 v[170:171], v[120:123], off
	s_nop 1
	v_and_b32_e32 v121, 64, v154
	v_xor_b32_e32 v120, 16, v154
	v_add_u32_e32 v121, 64, v121
	v_xor_b32_e32 v122, 32, v154
	v_cmp_lt_i32_e32 vcc, v120, v121
	v_mul_f32_e32 v123, v127, v127
	v_mul_f32_e32 v127, v159, v159
	v_cndmask_b32_e32 v120, v154, v120, vcc
	v_cmp_lt_i32_e32 vcc, v122, v121
	v_fmac_f32_e32 v123, v126, v126
	v_fmac_f32_e32 v127, v158, v158
	v_cndmask_b32_e32 v121, v154, v122, vcc
	v_mul_f32_e32 v122, v125, v125
	v_mul_f32_e32 v125, v157, v157
	v_fmac_f32_e32 v122, v124, v124
	v_fmac_f32_e32 v125, v156, v156
	v_add_f32_e32 v122, v122, v123
	v_add_f32_e32 v123, v125, v127
	v_add_f32_e32 v126, v122, v123
	v_lshlrev_b32_e32 v120, 2, v120
	s_waitcnt vmcnt(4)
	v_pk_add_f32 v[118:119], v[118:119], v[178:179]
	v_pk_add_f32 v[116:117], v[116:117], v[176:177]
	s_waitcnt vmcnt(3)
	v_pk_add_f32 v[124:125], v[114:115], v[182:183]
	v_pk_add_f32 v[122:123], v[112:113], v[180:181]
	v_mul_f32_e32 v112, v117, v117
	v_mul_f32_e32 v113, v119, v119
	v_mul_f32_e32 v114, v123, v123
	v_mul_f32_e32 v115, v125, v125
	v_fmac_f32_e32 v112, v116, v116
	v_fmac_f32_e32 v113, v118, v118
	v_fmac_f32_e32 v114, v122, v122
	v_fmac_f32_e32 v115, v124, v124
	v_add_f32_e32 v112, v112, v113
	v_add_f32_e32 v113, v114, v115
	v_add_f32_e32 v112, v112, v113
	v_add_f32_e32 v112, v126, v112
	ds_bpermute_b32 v113, v120, v112
	v_lshlrev_b32_e32 v114, 2, v121
	global_store_dwordx4 v[168:169], v[116:119], off offset:512 nt
	global_store_dwordx4 v[168:169], v[122:125], off offset:528 nt
	s_waitcnt lgkmcnt(0)
	v_add_f32_e32 v112, v112, v113
	ds_bpermute_b32 v113, v114, v112
	v_cvt_pk_bf16_f32 v116, v116, v117
	v_cvt_pk_bf16_f32 v117, v118, v119
	v_cvt_pk_bf16_f32 v118, v122, v123
	v_cvt_pk_bf16_f32 v119, v124, v125
	global_store_dwordx4 v[170:171], v[116:119], off offset:256
	s_and_saveexec_b64 s[24:25], s[2:3]
	s_cbranch_execz .LBB0_2087
	s_waitcnt lgkmcnt(0)
	v_add_f32_e32 v112, v112, v113
	v_mul_f32_e32 v112, 0x4b800000, v112
	v_trunc_f32_e32 v112, v112
	v_mul_f32_e32 v113, 0x2f800000, v112
	v_floor_f32_e32 v113, v113
	v_fmac_f32_e32 v112, 0xcf800000, v113
	v_cvt_u32_f32_e32 v112, v112
	v_cvt_u32_f32_e32 v113, v113
	v_lshl_add_u64 v[116:117], v[146:147], 3, s[6:7]
	global_atomic_add_x2 v[116:117], v[112:113], off
.LBB0_2087:
	s_or_b64 exec, exec, s[24:25]
	v_or_b32_e32 v112, 16, v146
	s_waitcnt lgkmcnt(0)
	v_ashrrev_i32_e32 v113, 31, v112
	v_lshlrev_b64 v[116:117], 11, v[112:113]
	v_lshl_add_u64 v[126:127], v[116:117], 0, v[144:145]
	v_lshl_add_u64 v[156:157], v[126:127], 2, s[28:29]
	global_load_dwordx4 v[116:119], v[156:157], off nt
	global_load_dwordx4 v[122:125], v[156:157], off offset:16 nt
	global_load_dwordx4 v[176:179], v[156:157], off offset:512 nt
	global_load_dwordx4 v[180:183], v[156:157], off offset:528 nt
	v_lshl_add_u64 v[126:127], v[126:127], 1, s[46:47]
	s_waitcnt vmcnt(3)
	v_pk_add_f32 v[110:111], v[110:111], v[118:119]
	v_pk_add_f32 v[108:109], v[108:109], v[116:117]
	s_waitcnt vmcnt(2)
	v_pk_add_f32 v[106:107], v[106:107], v[124:125]
	v_pk_add_f32 v[104:105], v[104:105], v[122:123]
	v_cvt_pk_bf16_f32 v116, v108, v109
	v_cvt_pk_bf16_f32 v117, v110, v111
	v_cvt_pk_bf16_f32 v118, v104, v105
	v_cvt_pk_bf16_f32 v119, v106, v107
	global_store_dwordx4 v[156:157], v[108:111], off nt
	global_store_dwordx4 v[156:157], v[104:107], off offset:16 nt
	global_store_dwordx4 v[126:127], v[116:119], off
	s_nop 1
	v_mul_f32_e32 v109, v109, v109
	v_mul_f32_e32 v111, v111, v111
	v_mul_f32_e32 v105, v105, v105
	v_mul_f32_e32 v107, v107, v107
	v_fmac_f32_e32 v109, v108, v108
	v_fmac_f32_e32 v111, v110, v110
	v_fmac_f32_e32 v105, v104, v104
	v_fmac_f32_e32 v107, v106, v106
	v_add_f32_e32 v104, v109, v111
	v_add_f32_e32 v105, v105, v107
	v_add_f32_e32 v108, v104, v105
	s_waitcnt vmcnt(4)
	v_pk_add_f32 v[102:103], v[102:103], v[178:179]
	v_pk_add_f32 v[100:101], v[100:101], v[176:177]
	s_waitcnt vmcnt(3)
	v_pk_add_f32 v[106:107], v[98:99], v[182:183]
	v_pk_add_f32 v[104:105], v[96:97], v[180:181]
	v_mul_f32_e32 v96, v101, v101
	v_mul_f32_e32 v97, v103, v103
	v_mul_f32_e32 v98, v105, v105
	v_mul_f32_e32 v99, v107, v107
	v_fmac_f32_e32 v96, v100, v100
	v_fmac_f32_e32 v97, v102, v102
	v_fmac_f32_e32 v98, v104, v104
	v_fmac_f32_e32 v99, v106, v106
	v_add_f32_e32 v96, v96, v97
	v_add_f32_e32 v97, v98, v99
	v_add_f32_e32 v96, v96, v97
	v_add_f32_e32 v96, v108, v96
	ds_bpermute_b32 v97, v120, v96
	global_store_dwordx4 v[156:157], v[100:103], off offset:512 nt
	global_store_dwordx4 v[156:157], v[104:107], off offset:528 nt
	v_cvt_pk_bf16_f32 v98, v100, v101
	v_cvt_pk_bf16_f32 v99, v102, v103
	v_cvt_pk_bf16_f32 v100, v104, v105
	s_waitcnt lgkmcnt(0)
	v_add_f32_e32 v96, v96, v97
	ds_bpermute_b32 v97, v114, v96
	v_cvt_pk_bf16_f32 v101, v106, v107
	global_store_dwordx4 v[126:127], v[98:101], off offset:256
	s_and_saveexec_b64 s[24:25], s[2:3]
	s_cbranch_execz .LBB0_2089
	s_waitcnt lgkmcnt(0)
	v_add_f32_e32 v96, v96, v97
	v_mul_f32_e32 v96, 0x4b800000, v96
	v_trunc_f32_e32 v96, v96
	v_mul_f32_e32 v97, 0x2f800000, v96
	v_floor_f32_e32 v97, v97
	v_fmac_f32_e32 v96, 0xcf800000, v97
	v_cvt_u32_f32_e32 v96, v96
	v_cvt_u32_f32_e32 v97, v97
	v_lshl_add_u64 v[98:99], v[112:113], 3, s[6:7]
	global_atomic_add_x2 v[98:99], v[96:97], off
; __device__ __forceinline__ u32x4 pack8(const f32x4 a, const f32x4 b) { u32x4 w; w.x = cvt_pk_bf16(a[0], a[1]); w.y = cvt_pk_bf16(a[2], a[3]); w.z = cvt_pk_bf16(b[0], b[1]); w.w = cvt_pk_bf16(b[2], b[3]); return w; }
; __device__ __forceinline__ void ss_add(ssq_t* p, float sq) { __hip_atomic_fetch_add(p, (ssq_t)(sq * 16777216.0f), __ATOMIC_RELAXED, __HIP_MEMORY_SCOPE_AGENT); }
; __device__ __forceinline__ float dot4(const f32x4 a) { return (a[0] * a[0] + a[1] * a[1]) + (a[2] * a[2] + a[3] * a[3]); }
;     __device__ __forceinline__ void operator()(const f32x4 (&acc)[2][2][4][2], const Unit& u, int wr, int wc, int fr, int fq) const {
;     ...
;             for (int m = 0; m < 4; ++m) { const int row = row0 + ai * HALF + m * 16; const size_t off = (size_t)row * 2048 + col0; float sq = 0.f;
; #pragma unroll
;                 for (int bj = 0; bj < 2; ++bj) {
;                     const f32x4 x0 = __builtin_nontemporal_load((const f32x4*)(xin + off + bj * HALF)), x1 = __builtin_nontemporal_load((const f32x4*)(xin + off + bj * HALF + 4));
;                     const f32x4 v0 = x0 + acc[ai][bj][m][0] * alpha, v1 = x1 + acc[ai][bj][m][1] * alpha;
;                     __builtin_nontemporal_store(v0, (f32x4*)(xout + off + bj * HALF)); __builtin_nontemporal_store(v1, (f32x4*)(xout + off + bj * HALF + 4));
;                     if (WRITE_XB) *(u32x4*)(xb + off + bj * HALF) = pack8(v0, v1); sq += dot4(v0) + dot4(v1); }
;                 sq += __shfl_xor(sq, 16); sq += __shfl_xor(sq, 32);
;                 if (fq == 0) ss_add(ssout + row, sq); }
.LBB0_2089:
	s_or_b64 exec, exec, s[24:25]
	v_or_b32_e32 v96, 32, v146
	s_waitcnt lgkmcnt(0)
	v_ashrrev_i32_e32 v97, 31, v96
	v_lshlrev_b64 v[98:99], 11, v[96:97]
	v_lshl_add_u64 v[106:107], v[98:99], 0, v[144:145]
	v_lshl_add_u64 v[108:109], v[106:107], 2, s[28:29]
	global_load_dwordx4 v[98:101], v[108:109], off nt
	global_load_dwordx4 v[102:105], v[108:109], off offset:16 nt
	global_load_dwordx4 v[176:179], v[108:109], off offset:512 nt
	global_load_dwordx4 v[180:183], v[108:109], off offset:528 nt
	v_lshl_add_u64 v[106:107], v[106:107], 1, s[46:47]
	s_waitcnt vmcnt(3)
	v_pk_add_f32 v[94:95], v[94:95], v[100:101]
	v_pk_add_f32 v[92:93], v[92:93], v[98:99]
	s_waitcnt vmcnt(2)
	v_pk_add_f32 v[90:91], v[90:91], v[104:105]
	v_pk_add_f32 v[88:89], v[88:89], v[102:103]
	v_cvt_pk_bf16_f32 v98, v92, v93
	v_cvt_pk_bf16_f32 v99, v94, v95
	v_cvt_pk_bf16_f32 v100, v88, v89
	v_cvt_pk_bf16_f32 v101, v90, v91
	global_store_dwordx4 v[108:109], v[92:95], off nt
	global_store_dwordx4 v[108:109], v[88:91], off offset:16 nt
	global_store_dwordx4 v[106:107], v[98:101], off
	s_nop 1
	v_mul_f32_e32 v93, v93, v93
	v_mul_f32_e32 v95, v95, v95
	v_mul_f32_e32 v89, v89, v89
	v_mul_f32_e32 v91, v91, v91
	v_fmac_f32_e32 v93, v92, v92
	v_fmac_f32_e32 v95, v94, v94
	v_fmac_f32_e32 v89, v88, v88
	v_fmac_f32_e32 v91, v90, v90
	v_add_f32_e32 v88, v93, v95
	v_add_f32_e32 v89, v89, v91
	v_add_f32_e32 v92, v88, v89
	s_waitcnt vmcnt(4)
	v_pk_add_f32 v[86:87], v[86:87], v[178:179]
	v_pk_add_f32 v[84:85], v[84:85], v[176:177]
	s_waitcnt vmcnt(3)
	v_pk_add_f32 v[90:91], v[82:83], v[182:183]
	v_pk_add_f32 v[88:89], v[80:81], v[180:181]
	v_mul_f32_e32 v80, v85, v85
	v_mul_f32_e32 v81, v87, v87
	v_mul_f32_e32 v82, v89, v89
	v_mul_f32_e32 v83, v91, v91
	v_fmac_f32_e32 v80, v84, v84
	v_fmac_f32_e32 v81, v86, v86
	v_fmac_f32_e32 v82, v88, v88
	v_fmac_f32_e32 v83, v90, v90
	v_add_f32_e32 v80, v80, v81
	v_add_f32_e32 v81, v82, v83
	v_add_f32_e32 v80, v80, v81
	v_add_f32_e32 v80, v92, v80
	ds_bpermute_b32 v81, v120, v80
	global_store_dwordx4 v[108:109], v[84:87], off offset:512 nt
	global_store_dwordx4 v[108:109], v[88:91], off offset:528 nt
	v_cvt_pk_bf16_f32 v82, v84, v85
	v_cvt_pk_bf16_f32 v83, v86, v87
	v_cvt_pk_bf16_f32 v84, v88, v89
	s_waitcnt lgkmcnt(0)
	v_add_f32_e32 v80, v80, v81
	ds_bpermute_b32 v81, v114, v80
	v_cvt_pk_bf16_f32 v85, v90, v91
	global_store_dwordx4 v[106:107], v[82:85], off offset:256
	s_and_saveexec_b64 s[24:25], s[2:3]
	s_cbranch_execz .LBB0_2091
	s_waitcnt lgkmcnt(0)
	v_add_f32_e32 v80, v80, v81
	v_mul_f32_e32 v80, 0x4b800000, v80
	v_trunc_f32_e32 v80, v80
	v_mul_f32_e32 v81, 0x2f800000, v80
	v_floor_f32_e32 v81, v81
	v_fmac_f32_e32 v80, 0xcf800000, v81
	v_cvt_u32_f32_e32 v80, v80
	v_cvt_u32_f32_e32 v81, v81
	v_lshl_add_u64 v[82:83], v[96:97], 3, s[6:7]
	global_atomic_add_x2 v[82:83], v[80:81], off
.LBB0_2091:
	s_or_b64 exec, exec, s[24:25]
	v_or_b32_e32 v80, 48, v146
	s_waitcnt lgkmcnt(0)
	v_ashrrev_i32_e32 v81, 31, v80
	v_lshlrev_b64 v[82:83], 11, v[80:81]
	v_lshl_add_u64 v[90:91], v[82:83], 0, v[144:145]
	v_lshl_add_u64 v[92:93], v[90:91], 2, s[28:29]
	global_load_dwordx4 v[82:85], v[92:93], off nt
	global_load_dwordx4 v[86:89], v[92:93], off offset:16 nt
	global_load_dwordx4 v[176:179], v[92:93], off offset:512 nt
	global_load_dwordx4 v[180:183], v[92:93], off offset:528 nt
	v_lshl_add_u64 v[90:91], v[90:91], 1, s[46:47]
	s_waitcnt vmcnt(3)
	v_pk_add_f32 v[78:79], v[78:79], v[84:85]
	v_pk_add_f32 v[76:77], v[76:77], v[82:83]
	s_waitcnt vmcnt(2)
	v_pk_add_f32 v[74:75], v[74:75], v[88:89]
	v_pk_add_f32 v[72:73], v[72:73], v[86:87]
	v_cvt_pk_bf16_f32 v82, v76, v77
	v_cvt_pk_bf16_f32 v83, v78, v79
	v_cvt_pk_bf16_f32 v84, v72, v73
	v_cvt_pk_bf16_f32 v85, v74, v75
	global_store_dwordx4 v[92:93], v[76:79], off nt
	global_store_dwordx4 v[92:93], v[72:75], off offset:16 nt
	global_store_dwordx4 v[90:91], v[82:85], off
	s_nop 1
	v_mul_f32_e32 v77, v77, v77
	v_mul_f32_e32 v79, v79, v79
	v_mul_f32_e32 v73, v73, v73
	v_mul_f32_e32 v75, v75, v75
	v_fmac_f32_e32 v77, v76, v76
	v_fmac_f32_e32 v79, v78, v78
	v_fmac_f32_e32 v73, v72, v72
	v_fmac_f32_e32 v75, v74, v74
	v_add_f32_e32 v72, v77, v79
	v_add_f32_e32 v73, v73, v75
	v_add_f32_e32 v76, v72, v73
	s_waitcnt vmcnt(4)
	v_pk_add_f32 v[70:71], v[70:71], v[178:179]
	v_pk_add_f32 v[68:69], v[68:69], v[176:177]
	s_waitcnt vmcnt(3)
	v_pk_add_f32 v[74:75], v[66:67], v[182:183]
	v_pk_add_f32 v[72:73], v[64:65], v[180:181]
	v_mul_f32_e32 v64, v69, v69
	v_mul_f32_e32 v65, v71, v71
	v_mul_f32_e32 v66, v73, v73
	v_mul_f32_e32 v67, v75, v75
	v_fmac_f32_e32 v64, v68, v68
	v_fmac_f32_e32 v65, v70, v70
	v_fmac_f32_e32 v66, v72, v72
	v_fmac_f32_e32 v67, v74, v74
	v_add_f32_e32 v64, v64, v65
	v_add_f32_e32 v65, v66, v67
	v_add_f32_e32 v64, v64, v65
	v_add_f32_e32 v64, v76, v64
	ds_bpermute_b32 v65, v120, v64
	global_store_dwordx4 v[92:93], v[68:71], off offset:512 nt
	global_store_dwordx4 v[92:93], v[72:75], off offset:528 nt
	v_cvt_pk_bf16_f32 v66, v68, v69
	v_cvt_pk_bf16_f32 v67, v70, v71
	v_cvt_pk_bf16_f32 v68, v72, v73
	s_waitcnt lgkmcnt(0)
	v_add_f32_e32 v64, v64, v65
	ds_bpermute_b32 v65, v114, v64
	v_cvt_pk_bf16_f32 v69, v74, v75
	global_store_dwordx4 v[90:91], v[66:69], off offset:256
	s_and_saveexec_b64 s[24:25], s[2:3]
	s_cbranch_execz .LBB0_2093
	s_waitcnt lgkmcnt(0)
	v_add_f32_e32 v64, v64, v65
	v_mul_f32_e32 v64, 0x4b800000, v64
	v_trunc_f32_e32 v64, v64
	v_mul_f32_e32 v65, 0x2f800000, v64
	v_floor_f32_e32 v65, v65
	v_fmac_f32_e32 v64, 0xcf800000, v65
	v_cvt_u32_f32_e32 v64, v64
	v_cvt_u32_f32_e32 v65, v65
	v_lshl_add_u64 v[66:67], v[80:81], 3, s[6:7]
	global_atomic_add_x2 v[66:67], v[64:65], off
; __device__ __forceinline__ u32x4 pack8(const f32x4 a, const f32x4 b) { u32x4 w; w.x = cvt_pk_bf16(a[0], a[1]); w.y = cvt_pk_bf16(a[2], a[3]); w.z = cvt_pk_bf16(b[0], b[1]); w.w = cvt_pk_bf16(b[2], b[3]); return w; }
; __device__ __forceinline__ void ss_add(ssq_t* p, float sq) { __hip_atomic_fetch_add(p, (ssq_t)(sq * 16777216.0f), __ATOMIC_RELAXED, __HIP_MEMORY_SCOPE_AGENT); }
; __device__ __forceinline__ float dot4(const f32x4 a) { return (a[0] * a[0] + a[1] * a[1]) + (a[2] * a[2] + a[3] * a[3]); }
;     __device__ __forceinline__ void operator()(const f32x4 (&acc)[2][2][4][2], const Unit& u, int wr, int wc, int fr, int fq) const {
;     ...
;             for (int m = 0; m < 4; ++m) { const int row = row0 + ai * HALF + m * 16; const size_t off = (size_t)row * 2048 + col0; float sq = 0.f;
; #pragma unroll
;                 for (int bj = 0; bj < 2; ++bj) {
;                     const f32x4 x0 = __builtin_nontemporal_load((const f32x4*)(xin + off + bj * HALF)), x1 = __builtin_nontemporal_load((const f32x4*)(xin + off + bj * HALF + 4));
;                     const f32x4 v0 = x0 + acc[ai][bj][m][0] * alpha, v1 = x1 + acc[ai][bj][m][1] * alpha;
;                     __builtin_nontemporal_store(v0, (f32x4*)(xout + off + bj * HALF)); __builtin_nontemporal_store(v1, (f32x4*)(xout + off + bj * HALF + 4));
;                     if (WRITE_XB) *(u32x4*)(xb + off + bj * HALF) = pack8(v0, v1); sq += dot4(v0) + dot4(v1); }
;                 sq += __shfl_xor(sq, 16); sq += __shfl_xor(sq, 32);
;                 if (fq == 0) ss_add(ssout + row, sq); }
.LBB0_2093:
	s_or_b64 exec, exec, s[24:25]
	v_add_u32_e32 v64, 0x80, v146
	s_waitcnt lgkmcnt(0)
	v_ashrrev_i32_e32 v65, 31, v64
	v_lshlrev_b64 v[66:67], 11, v[64:65]
	v_lshl_add_u64 v[74:75], v[66:67], 0, v[144:145]
	v_lshl_add_u64 v[76:77], v[74:75], 2, s[28:29]
	global_load_dwordx4 v[66:69], v[76:77], off nt
	global_load_dwordx4 v[70:73], v[76:77], off offset:16 nt
	global_load_dwordx4 v[176:179], v[76:77], off offset:512 nt
	global_load_dwordx4 v[180:183], v[76:77], off offset:528 nt
	v_lshl_add_u64 v[74:75], v[74:75], 1, s[46:47]
	s_waitcnt vmcnt(3)
	v_pk_add_f32 v[62:63], v[62:63], v[68:69]
	v_pk_add_f32 v[60:61], v[60:61], v[66:67]
	s_waitcnt vmcnt(2)
	v_pk_add_f32 v[58:59], v[58:59], v[72:73]
	v_pk_add_f32 v[56:57], v[56:57], v[70:71]
	v_cvt_pk_bf16_f32 v66, v60, v61
	v_cvt_pk_bf16_f32 v67, v62, v63
	v_cvt_pk_bf16_f32 v68, v56, v57
	v_cvt_pk_bf16_f32 v69, v58, v59
	global_store_dwordx4 v[76:77], v[60:63], off nt
	global_store_dwordx4 v[76:77], v[56:59], off offset:16 nt
	global_store_dwordx4 v[74:75], v[66:69], off
	s_nop 1
	v_mul_f32_e32 v61, v61, v61
	v_mul_f32_e32 v63, v63, v63
	v_mul_f32_e32 v57, v57, v57
	v_mul_f32_e32 v59, v59, v59
	v_fmac_f32_e32 v61, v60, v60
	v_fmac_f32_e32 v63, v62, v62
	v_fmac_f32_e32 v57, v56, v56
	v_fmac_f32_e32 v59, v58, v58
	v_add_f32_e32 v56, v61, v63
	v_add_f32_e32 v57, v57, v59
	v_add_f32_e32 v60, v56, v57
	s_waitcnt vmcnt(4)
	v_pk_add_f32 v[54:55], v[54:55], v[178:179]
	v_pk_add_f32 v[52:53], v[52:53], v[176:177]
	s_waitcnt vmcnt(3)
	v_pk_add_f32 v[58:59], v[50:51], v[182:183]
	v_pk_add_f32 v[56:57], v[48:49], v[180:181]
	v_mul_f32_e32 v48, v53, v53
	v_mul_f32_e32 v49, v55, v55
	v_mul_f32_e32 v50, v57, v57
	v_mul_f32_e32 v51, v59, v59
	v_fmac_f32_e32 v48, v52, v52
	v_fmac_f32_e32 v49, v54, v54
	v_fmac_f32_e32 v50, v56, v56
	v_fmac_f32_e32 v51, v58, v58
	v_add_f32_e32 v48, v48, v49
	v_add_f32_e32 v49, v50, v51
	v_add_f32_e32 v48, v48, v49
	v_add_f32_e32 v48, v60, v48
	ds_bpermute_b32 v49, v120, v48
	global_store_dwordx4 v[76:77], v[52:55], off offset:512 nt
	global_store_dwordx4 v[76:77], v[56:59], off offset:528 nt
	v_cvt_pk_bf16_f32 v50, v52, v53
	v_cvt_pk_bf16_f32 v51, v54, v55
	v_cvt_pk_bf16_f32 v52, v56, v57
	s_waitcnt lgkmcnt(0)
	v_add_f32_e32 v48, v48, v49
	ds_bpermute_b32 v49, v114, v48
	v_cvt_pk_bf16_f32 v53, v58, v59
	global_store_dwordx4 v[74:75], v[50:53], off offset:256
	s_and_saveexec_b64 s[24:25], s[2:3]
	s_cbranch_execz .LBB0_2095
	s_waitcnt lgkmcnt(0)
	v_add_f32_e32 v48, v48, v49
	v_mul_f32_e32 v48, 0x4b800000, v48
	v_trunc_f32_e32 v48, v48
	v_mul_f32_e32 v49, 0x2f800000, v48
	v_floor_f32_e32 v49, v49
	v_fmac_f32_e32 v48, 0xcf800000, v49
	v_cvt_u32_f32_e32 v48, v48
	v_cvt_u32_f32_e32 v49, v49
	v_lshl_add_u64 v[50:51], v[64:65], 3, s[6:7]
	global_atomic_add_x2 v[50:51], v[48:49], off
.LBB0_2095:
	s_or_b64 exec, exec, s[24:25]
	v_add_u32_e32 v48, 0x90, v146
	s_waitcnt lgkmcnt(0)
	v_ashrrev_i32_e32 v49, 31, v48
	v_lshlrev_b64 v[50:51], 11, v[48:49]
	v_lshl_add_u64 v[58:59], v[50:51], 0, v[144:145]
	v_lshl_add_u64 v[60:61], v[58:59], 2, s[28:29]
	global_load_dwordx4 v[50:53], v[60:61], off nt
	global_load_dwordx4 v[54:57], v[60:61], off offset:16 nt
	global_load_dwordx4 v[176:179], v[60:61], off offset:512 nt
	global_load_dwordx4 v[180:183], v[60:61], off offset:528 nt
	v_lshl_add_u64 v[58:59], v[58:59], 1, s[46:47]
	s_waitcnt vmcnt(3)
	v_pk_add_f32 v[46:47], v[46:47], v[52:53]
	v_pk_add_f32 v[44:45], v[44:45], v[50:51]
	s_waitcnt vmcnt(2)
	v_pk_add_f32 v[42:43], v[42:43], v[56:57]
	v_pk_add_f32 v[40:41], v[40:41], v[54:55]
	v_cvt_pk_bf16_f32 v50, v44, v45
	v_cvt_pk_bf16_f32 v51, v46, v47
	v_cvt_pk_bf16_f32 v52, v40, v41
	v_cvt_pk_bf16_f32 v53, v42, v43
	global_store_dwordx4 v[60:61], v[44:47], off nt
	global_store_dwordx4 v[60:61], v[40:43], off offset:16 nt
	global_store_dwordx4 v[58:59], v[50:53], off
	s_nop 1
	v_mul_f32_e32 v45, v45, v45
	v_mul_f32_e32 v47, v47, v47
	v_mul_f32_e32 v41, v41, v41
	v_mul_f32_e32 v43, v43, v43
	v_fmac_f32_e32 v45, v44, v44
	v_fmac_f32_e32 v47, v46, v46
	v_fmac_f32_e32 v41, v40, v40
	v_fmac_f32_e32 v43, v42, v42
	v_add_f32_e32 v40, v45, v47
	v_add_f32_e32 v41, v41, v43
	v_add_f32_e32 v44, v40, v41
	s_waitcnt vmcnt(4)
	v_pk_add_f32 v[38:39], v[38:39], v[178:179]
	v_pk_add_f32 v[36:37], v[36:37], v[176:177]
	s_waitcnt vmcnt(3)
	v_pk_add_f32 v[42:43], v[34:35], v[182:183]
	v_pk_add_f32 v[40:41], v[32:33], v[180:181]
	v_mul_f32_e32 v32, v37, v37
	v_mul_f32_e32 v33, v39, v39
	v_mul_f32_e32 v34, v41, v41
	v_mul_f32_e32 v35, v43, v43
	v_fmac_f32_e32 v32, v36, v36
	v_fmac_f32_e32 v33, v38, v38
	v_fmac_f32_e32 v34, v40, v40
	v_fmac_f32_e32 v35, v42, v42
	v_add_f32_e32 v32, v32, v33
	v_add_f32_e32 v33, v34, v35
	v_add_f32_e32 v32, v32, v33
	v_add_f32_e32 v32, v44, v32
	ds_bpermute_b32 v33, v120, v32
	global_store_dwordx4 v[60:61], v[36:39], off offset:512 nt
	global_store_dwordx4 v[60:61], v[40:43], off offset:528 nt
	v_cvt_pk_bf16_f32 v34, v36, v37
	v_cvt_pk_bf16_f32 v35, v38, v39
	v_cvt_pk_bf16_f32 v36, v40, v41
	s_waitcnt lgkmcnt(0)
	v_add_f32_e32 v32, v32, v33
	ds_bpermute_b32 v33, v114, v32
	v_cvt_pk_bf16_f32 v37, v42, v43
	global_store_dwordx4 v[58:59], v[34:37], off offset:256
	s_and_saveexec_b64 s[24:25], s[2:3]
	s_cbranch_execz .LBB0_2097
	s_waitcnt lgkmcnt(0)
	v_add_f32_e32 v32, v32, v33
	v_mul_f32_e32 v32, 0x4b800000, v32
	v_trunc_f32_e32 v32, v32
	v_mul_f32_e32 v33, 0x2f800000, v32
	v_floor_f32_e32 v33, v33
	v_fmac_f32_e32 v32, 0xcf800000, v33
	v_cvt_u32_f32_e32 v32, v32
	v_cvt_u32_f32_e32 v33, v33
	v_lshl_add_u64 v[34:35], v[48:49], 3, s[6:7]
	global_atomic_add_x2 v[34:35], v[32:33], off
; __device__ __forceinline__ u32x4 pack8(const f32x4 a, const f32x4 b) { u32x4 w; w.x = cvt_pk_bf16(a[0], a[1]); w.y = cvt_pk_bf16(a[2], a[3]); w.z = cvt_pk_bf16(b[0], b[1]); w.w = cvt_pk_bf16(b[2], b[3]); return w; }
; __device__ __forceinline__ void ss_add(ssq_t* p, float sq) { __hip_atomic_fetch_add(p, (ssq_t)(sq * 16777216.0f), __ATOMIC_RELAXED, __HIP_MEMORY_SCOPE_AGENT); }
; __device__ __forceinline__ float dot4(const f32x4 a) { return (a[0] * a[0] + a[1] * a[1]) + (a[2] * a[2] + a[3] * a[3]); }
;     __device__ __forceinline__ void operator()(const f32x4 (&acc)[2][2][4][2], const Unit& u, int wr, int wc, int fr, int fq) const {
;     ...
;             for (int m = 0; m < 4; ++m) { const int row = row0 + ai * HALF + m * 16; const size_t off = (size_t)row * 2048 + col0; float sq = 0.f;
; #pragma unroll
;                 for (int bj = 0; bj < 2; ++bj) {
;                     const f32x4 x0 = __builtin_nontemporal_load((const f32x4*)(xin + off + bj * HALF)), x1 = __builtin_nontemporal_load((const f32x4*)(xin + off + bj * HALF + 4));
;                     const f32x4 v0 = x0 + acc[ai][bj][m][0] * alpha, v1 = x1 + acc[ai][bj][m][1] * alpha;
;                     __builtin_nontemporal_store(v0, (f32x4*)(xout + off + bj * HALF)); __builtin_nontemporal_store(v1, (f32x4*)(xout + off + bj * HALF + 4));
;                     if (WRITE_XB) *(u32x4*)(xb + off + bj * HALF) = pack8(v0, v1); sq += dot4(v0) + dot4(v1); }
;                 sq += __shfl_xor(sq, 16); sq += __shfl_xor(sq, 32);
;                 if (fq == 0) ss_add(ssout + row, sq); }
.LBB0_2097:
	s_or_b64 exec, exec, s[24:25]
	v_add_u32_e32 v32, 0xa0, v146
	s_waitcnt lgkmcnt(0)
	v_ashrrev_i32_e32 v33, 31, v32
	v_lshlrev_b64 v[34:35], 11, v[32:33]
	v_lshl_add_u64 v[42:43], v[34:35], 0, v[144:145]
	v_lshl_add_u64 v[44:45], v[42:43], 2, s[28:29]
	global_load_dwordx4 v[34:37], v[44:45], off nt
	global_load_dwordx4 v[38:41], v[44:45], off offset:16 nt
	global_load_dwordx4 v[176:179], v[44:45], off offset:512 nt
	global_load_dwordx4 v[180:183], v[44:45], off offset:528 nt
	v_lshl_add_u64 v[42:43], v[42:43], 1, s[46:47]
	s_waitcnt vmcnt(3)
	v_pk_add_f32 v[30:31], v[30:31], v[36:37]
	v_pk_add_f32 v[28:29], v[28:29], v[34:35]
	s_waitcnt vmcnt(2)
	v_pk_add_f32 v[26:27], v[26:27], v[40:41]
	v_pk_add_f32 v[24:25], v[24:25], v[38:39]
	v_cvt_pk_bf16_f32 v34, v28, v29
	v_cvt_pk_bf16_f32 v35, v30, v31
	v_cvt_pk_bf16_f32 v36, v24, v25
	v_cvt_pk_bf16_f32 v37, v26, v27
	global_store_dwordx4 v[44:45], v[28:31], off nt
	global_store_dwordx4 v[44:45], v[24:27], off offset:16 nt
	global_store_dwordx4 v[42:43], v[34:37], off
	s_nop 1
	v_mul_f32_e32 v29, v29, v29
	v_mul_f32_e32 v31, v31, v31
	v_mul_f32_e32 v25, v25, v25
	v_mul_f32_e32 v27, v27, v27
	v_fmac_f32_e32 v29, v28, v28
	v_fmac_f32_e32 v31, v30, v30
	v_fmac_f32_e32 v25, v24, v24
	v_fmac_f32_e32 v27, v26, v26
	v_add_f32_e32 v24, v29, v31
	v_add_f32_e32 v25, v25, v27
	v_add_f32_e32 v28, v24, v25
	s_waitcnt vmcnt(4)
	v_pk_add_f32 v[22:23], v[22:23], v[178:179]
	v_pk_add_f32 v[20:21], v[20:21], v[176:177]
	s_waitcnt vmcnt(3)
	v_pk_add_f32 v[26:27], v[18:19], v[182:183]
	v_pk_add_f32 v[24:25], v[16:17], v[180:181]
	v_mul_f32_e32 v16, v21, v21
	v_mul_f32_e32 v17, v23, v23
	v_mul_f32_e32 v18, v25, v25
	v_mul_f32_e32 v19, v27, v27
	v_fmac_f32_e32 v16, v20, v20
	v_fmac_f32_e32 v17, v22, v22
	v_fmac_f32_e32 v18, v24, v24
	v_fmac_f32_e32 v19, v26, v26
	v_add_f32_e32 v16, v16, v17
	v_add_f32_e32 v17, v18, v19
	v_add_f32_e32 v16, v16, v17
	v_add_f32_e32 v16, v28, v16
	ds_bpermute_b32 v17, v120, v16
	global_store_dwordx4 v[44:45], v[20:23], off offset:512 nt
	global_store_dwordx4 v[44:45], v[24:27], off offset:528 nt
	v_cvt_pk_bf16_f32 v18, v20, v21
	v_cvt_pk_bf16_f32 v19, v22, v23
	v_cvt_pk_bf16_f32 v20, v24, v25
	s_waitcnt lgkmcnt(0)
	v_add_f32_e32 v16, v16, v17
	ds_bpermute_b32 v17, v114, v16
	v_cvt_pk_bf16_f32 v21, v26, v27
	global_store_dwordx4 v[42:43], v[18:21], off offset:256
	s_and_saveexec_b64 s[24:25], s[2:3]
	s_cbranch_execz .LBB0_2099
	s_waitcnt lgkmcnt(0)
	v_add_f32_e32 v16, v16, v17
	v_mul_f32_e32 v16, 0x4b800000, v16
	v_trunc_f32_e32 v16, v16
	v_mul_f32_e32 v17, 0x2f800000, v16
	v_floor_f32_e32 v17, v17
	v_fmac_f32_e32 v16, 0xcf800000, v17
	v_cvt_u32_f32_e32 v16, v16
	v_cvt_u32_f32_e32 v17, v17
	v_lshl_add_u64 v[18:19], v[32:33], 3, s[6:7]
	global_atomic_add_x2 v[18:19], v[16:17], off
.LBB0_2099:
	s_or_b64 exec, exec, s[24:25]
	v_add_u32_e32 v16, 0xb0, v146
	s_waitcnt lgkmcnt(0)
	v_ashrrev_i32_e32 v17, 31, v16
	v_lshlrev_b64 v[18:19], 11, v[16:17]
	v_lshl_add_u64 v[26:27], v[18:19], 0, v[144:145]
	v_lshl_add_u64 v[28:29], v[26:27], 2, s[28:29]
	global_load_dwordx4 v[18:21], v[28:29], off nt
	global_load_dwordx4 v[22:25], v[28:29], off offset:16 nt
	global_load_dwordx4 v[176:179], v[28:29], off offset:512 nt
	global_load_dwordx4 v[180:183], v[28:29], off offset:528 nt
	v_lshl_add_u64 v[26:27], v[26:27], 1, s[46:47]
	s_waitcnt vmcnt(3)
	v_pk_add_f32 v[14:15], v[14:15], v[20:21]
	v_pk_add_f32 v[12:13], v[12:13], v[18:19]
	s_waitcnt vmcnt(2)
	v_pk_add_f32 v[10:11], v[10:11], v[24:25]
	v_pk_add_f32 v[8:9], v[8:9], v[22:23]
	v_cvt_pk_bf16_f32 v18, v12, v13
	v_cvt_pk_bf16_f32 v19, v14, v15
	v_cvt_pk_bf16_f32 v20, v8, v9
	v_cvt_pk_bf16_f32 v21, v10, v11
	global_store_dwordx4 v[28:29], v[12:15], off nt
	global_store_dwordx4 v[28:29], v[8:11], off offset:16 nt
	global_store_dwordx4 v[26:27], v[18:21], off
	s_nop 1
	v_mul_f32_e32 v13, v13, v13
	v_mul_f32_e32 v15, v15, v15
	v_mul_f32_e32 v9, v9, v9
	v_mul_f32_e32 v11, v11, v11
	v_fmac_f32_e32 v13, v12, v12
	v_fmac_f32_e32 v15, v14, v14
	v_fmac_f32_e32 v9, v8, v8
	v_fmac_f32_e32 v11, v10, v10
	v_add_f32_e32 v8, v13, v15
	v_add_f32_e32 v9, v9, v11
	v_add_f32_e32 v12, v8, v9
	s_waitcnt vmcnt(4)
	v_pk_add_f32 v[6:7], v[6:7], v[178:179]
	v_pk_add_f32 v[4:5], v[4:5], v[176:177]
	s_waitcnt vmcnt(3)
	v_pk_add_f32 v[10:11], v[2:3], v[182:183]
	v_pk_add_f32 v[8:9], v[0:1], v[180:181]
	v_mul_f32_e32 v0, v5, v5
	v_mul_f32_e32 v1, v7, v7
	v_mul_f32_e32 v2, v9, v9
	v_mul_f32_e32 v3, v11, v11
	v_fmac_f32_e32 v0, v4, v4
	v_fmac_f32_e32 v1, v6, v6
	v_fmac_f32_e32 v2, v8, v8
	v_fmac_f32_e32 v3, v10, v10
	v_add_f32_e32 v0, v0, v1
	v_add_f32_e32 v1, v2, v3
	v_add_f32_e32 v0, v0, v1
	v_add_f32_e32 v0, v12, v0
	ds_bpermute_b32 v1, v120, v0
	global_store_dwordx4 v[28:29], v[4:7], off offset:512 nt
	global_store_dwordx4 v[28:29], v[8:11], off offset:528 nt
	v_cvt_pk_bf16_f32 v2, v4, v5
	v_cvt_pk_bf16_f32 v3, v6, v7
	v_cvt_pk_bf16_f32 v4, v8, v9
	s_waitcnt lgkmcnt(0)
	v_add_f32_e32 v0, v0, v1
	ds_bpermute_b32 v1, v114, v0
	v_cvt_pk_bf16_f32 v5, v10, v11
	global_store_dwordx4 v[26:27], v[2:5], off offset:256
	s_and_saveexec_b64 s[24:25], s[2:3]
	s_cbranch_execz .LBB0_2101
	s_waitcnt lgkmcnt(0)
	v_add_f32_e32 v0, v0, v1
	v_mul_f32_e32 v0, 0x4b800000, v0
	v_trunc_f32_e32 v0, v0
	v_mul_f32_e32 v1, 0x2f800000, v0
	v_floor_f32_e32 v1, v1
	v_fmac_f32_e32 v0, 0xcf800000, v1
	v_cvt_u32_f32_e32 v0, v0
	v_cvt_u32_f32_e32 v1, v1
	v_lshl_add_u64 v[2:3], v[16:17], 3, s[6:7]
	global_atomic_add_x2 v[2:3], v[0:1], off
